# v67 + sample-row publish atomic moved from before the out_proj/down GEMM to after the GEMM drain barrier (removes a vmcnt(0)+barrier+thread-0 block from the pre-GEMM path)
# baseline (speedup 1.0000x reference)
;     __host__ __device__ bool next(int i, Unit& u) const {
;         const long L = (long)i * G + c; if (L >= nwg) return false;
;         int wgid = (int)L; { const int q = nwg / NXCD, r = nwg % NXCD, xcd = wgid % NXCD, off = wgid / NXCD; wgid = (xcd < r ? xcd * (q + 1) : r * (q + 1) + (xcd - r) * q) + off; }
;         const int nig = WGM * nN, gid = wgid / nig, fm = gid * WGM, gsz = (nM - fm) < WGM ? (nM - fm) : WGM;
;         u.pm = fm + ((wgid % nig) % gsz); u.pn = (wgid % nig) / gsz; return true;
.LBB0_1026:
	v_readlane_b32 s4, v252, 1
	s_add_u32 s14, s66, 0x30f00000
	v_readlane_b32 s5, v252, 2
	s_addc_u32 s15, s67, 0
	s_mov_b64 s[0:1], s[4:5]
	v_mov_b32_e32 v8, v172
	s_cmpk_lt_i32 s2, 0x100
	s_cselect_b64 s[16:17], -1, 0
	s_cmpk_gt_i32 s2, 0xff
	v_readfirstlane_b32 s21, v8
	s_cbranch_scc1 .LBB0_1070
	s_ashr_i32 s48, s2, 31
	s_lshr_b32 s6, s48, 29
	s_add_i32 s8, s2, s6
	s_and_b32 s6, s8, -8
	s_sub_i32 s11, s2, s6
	s_cmp_gt_i32 s11, -1
	s_cbranch_scc0 .LBB0_1029
	s_lshl_b32 s9, s11, 5
	s_cbranch_execz .LBB0_1030
	s_branch .LBB0_1031

; __device__ __forceinline__ unsigned xb_add(unsigned* p, unsigned v) { return __hip_atomic_fetch_add(p, v, __ATOMIC_RELAXED, __HIP_MEMORY_SCOPE_AGENT); }
;     __device__ __forceinline__ void fused(f32x4 (&acc)[2][2][4][2], const Unit& u, int wr, int wc, int fr, int fq, PG8_LAS unsigned char* lds, int wid, int lane) const {
;     ...
;         for (int ai = 0; ai < 2; ++ai)
; #pragma unroll
;             for (int m = 0; m < 4; ++m) {
;                 const int rl = ai * 128 + wr * 64 + m * 16 + fr;
;                 const size_t roff = (size_t)(u.pm * 256 + rl) * 1024 + u.pn * 256 + wc * 32 + fq * 8;
;                 float s1 = 0.f, s2 = 0.f;
; #pragma unroll
;                 for (int bj = 0; bj < 2; ++bj) {
;                     float x[8];
;                     if (RES_BF16) ld8f((const bfu*)res + roff + bj * 128, x);
;                     else ld8f32((const float*)res + roff + bj * 128, x);
; #pragma unroll
;                     for (int n = 0; n < 2; ++n) {
;                         f32x4 v = acc[ai][bj][m][n];
;                         v[0] += ALPHA * x[4 * n]; v[1] += ALPHA * x[4 * n + 1]; v[2] += ALPHA * x[4 * n + 2]; v[3] += ALPHA * x[4 * n + 3];
;                         acc[ai][bj][m][n] = v;
;                         s1 += (v[0] + v[1]) + (v[2] + v[3]); s2 += (v[0] * v[0] + v[1] * v[1]) + (v[2] * v[2] + v[3] * v[3]);
;                     }
;                 }
;                 s1 += __shfl_xor(s1, 16); s1 += __shfl_xor(s1, 32); s2 += __shfl_xor(s2, 16); s2 += __shfl_xor(s2, 32);
; __device__ __forceinline__ void sample_rows_publish(unsigned* cnt_s, int bid) {
;     ...
;     if (threadIdx.x == 0) { __builtin_amdgcn_fence(__ATOMIC_RELEASE, "agent"); asm volatile("s_waitcnt vmcnt(0)" ::: "memory"); xb_add(cnt_s + (bid >> 4) * 64, 1u); }
.LBB0_1048:
	s_add_u32 s22, s66, 0x38b00000
	s_addc_u32 s23, s67, 0
	s_lshl_b32 s19, s18, 8
	v_add_u32_e32 v142, s19, v129
	s_lshl_b32 s8, s20, 8
	v_ashrrev_i32_e32 v143, 31, v142
	v_readlane_b32 s28, v252, 8
	s_ashr_i32 s9, s8, 31
	v_lshlrev_b64 v[142:143], 11, v[142:143]
	v_readlane_b32 s29, v252, 9
	s_lshl_b64 s[26:27], s[8:9], 1
	s_mov_b32 s25, 0
	v_lshl_add_u64 v[144:145], s[28:29], 0, v[142:143]
	v_lshl_add_u64 v[144:145], v[144:145], 0, s[26:27]
	s_lshl_b32 s24, s11, 6
	v_lshl_add_u64 v[144:145], v[144:145], 0, s[24:25]
	v_mov_b32_e32 v141, 0
	v_lshl_add_u64 v[144:145], v[144:145], 0, v[140:141]
	s_barrier
	global_load_dwordx4 v[146:149], v[144:145], off
	global_load_dwordx4 v[150:153], v[144:145], off offset:256
	s_mov_b64 s[98:99], 0x8000
	v_lshl_add_u64 v[250:251], v[144:145], 0, s[98:99]
	global_load_dwordx4 v[210:213], v[250:251], off
	global_load_dwordx4 v[214:217], v[250:251], off offset:256
	s_mov_b64 s[98:99], 0x10000
	v_lshl_add_u64 v[250:251], v[144:145], 0, s[98:99]
	global_load_dwordx4 v[218:221], v[250:251], off
	global_load_dwordx4 v[222:225], v[250:251], off offset:256
	s_mov_b64 s[98:99], 0x18000
	v_lshl_add_u64 v[250:251], v[144:145], 0, s[98:99]
	global_load_dwordx4 v[226:229], v[250:251], off
	global_load_dwordx4 v[230:233], v[250:251], off offset:256
	s_mov_b64 s[98:99], 0x40000
	v_lshl_add_u64 v[250:251], v[144:145], 0, s[98:99]
	global_load_dwordx4 v[234:237], v[250:251], off
	global_load_dwordx4 v[238:241], v[250:251], off offset:256
	s_mov_b64 s[98:99], 0x48000
	v_lshl_add_u64 v[250:251], v[144:145], 0, s[98:99]
	global_load_dwordx4 v[242:245], v[250:251], off
	global_load_dwordx4 v[246:249], v[250:251], off offset:256
	v_readlane_b32 s98, v252, 6
	v_readlane_b32 s99, v252, 7
	s_nop 3
	s_and_saveexec_b64 s[100:101], s[98:99]
	s_cbranch_execz .Lpub_skip_p7
	s_lshl_b32 s98, s2, 2
	s_andn2_b32 s98, s98, 63
	s_lshl_b32 s98, s98, 2
	s_add_u32 s98, s3, s98
	s_addc_u32 s99, s33, 0
	v_mov_b32_e32 v250, 0
	v_mov_b32_e32 v251, 1
	global_atomic_add v250, v251, s[98:99]
.Lpub_skip_p7:
	s_mov_b64 exec, s[100:101]
	v_mbcnt_lo_u32_b32 v144, -1, 0
	v_mbcnt_hi_u32_b32 v154, -1, v144
	v_and_b32_e32 v145, 64, v154
	v_or_b32_e32 v178, 16, v129
	v_xor_b32_e32 v155, 16, v154
	v_add_u32_e32 v157, 64, v145
	v_xor_b32_e32 v156, 32, v154
	v_add_u32_e32 v144, s19, v178
	v_cmp_lt_i32_e32 vcc, v155, v157
	v_ashrrev_i32_e32 v145, 31, v144
	v_lshlrev_b64 v[144:145], 11, v[144:145]
	v_cndmask_b32_e32 v155, v154, v155, vcc
	v_cmp_lt_i32_e32 vcc, v156, v157
	v_lshlrev_b32_e32 v181, 2, v155
	s_mov_b32 s6, 0x3f9837f0
	v_cndmask_b32_e32 v154, v154, v156, vcc
	v_lshlrev_b32_e32 v180, 2, v154
	v_lshl_add_u64 v[154:155], s[28:29], 0, v[144:145]
	v_lshl_add_u64 v[154:155], v[154:155], 0, s[26:27]
	v_lshl_add_u64 v[154:155], v[154:155], 0, s[24:25]
	v_lshl_add_u64 v[158:159], v[154:155], 0, v[140:141]
	s_waitcnt vmcnt(0)
	v_mov_b64_e32 v[154:155], v[210:211]
	v_mov_b64_e32 v[156:157], v[212:213]
	s_nop 0
	v_mov_b64_e32 v[158:159], v[214:215]
	v_mov_b64_e32 v[160:161], v[216:217]
	v_or_b32_e32 v179, 32, v129
	v_lshl_add_u32 v177, v172, 3, 0
	v_cmp_eq_u32_e32 vcc, 0, v176
	s_waitcnt vmcnt(0)
	v_lshlrev_b32_e32 v162, 16, v146
	v_and_b32_e32 v163, 0xffff0000, v146
	v_lshlrev_b32_e32 v164, 16, v147
	v_and_b32_e32 v165, 0xffff0000, v147
	v_lshlrev_b32_e32 v166, 16, v148
	v_and_b32_e32 v167, 0xffff0000, v148
	v_lshlrev_b32_e32 v148, 16, v149
	v_and_b32_e32 v149, 0xffff0000, v149
	v_lshlrev_b32_e32 v168, 16, v150
	v_and_b32_e32 v169, 0xffff0000, v150
	v_lshlrev_b32_e32 v150, 16, v151
	v_and_b32_e32 v151, 0xffff0000, v151
	v_lshlrev_b32_e32 v170, 16, v152
	v_and_b32_e32 v171, 0xffff0000, v152
	v_lshlrev_b32_e32 v152, 16, v153
	v_and_b32_e32 v153, 0xffff0000, v153
	v_pk_fma_f32 v[146:147], v[162:163], s[6:7], v[124:125] op_sel_hi:[1,0,1]
	v_pk_fma_f32 v[124:125], v[164:165], s[6:7], v[126:127] op_sel_hi:[1,0,1]
	v_pk_fma_f32 v[126:127], v[166:167], s[6:7], v[120:121] op_sel_hi:[1,0,1]
	v_pk_fma_f32 v[122:123], v[148:149], s[6:7], v[122:123] op_sel_hi:[1,0,1]
	v_pk_fma_f32 v[120:121], v[168:169], s[6:7], v[116:117] op_sel_hi:[1,0,1]
	v_pk_fma_f32 v[116:117], v[150:151], s[6:7], v[118:119] op_sel_hi:[1,0,1]
	v_pk_fma_f32 v[118:119], v[170:171], s[6:7], v[112:113] op_sel_hi:[1,0,1]
	v_pk_fma_f32 v[112:113], v[152:153], s[6:7], v[114:115] op_sel_hi:[1,0,1]
	v_pk_add_f32 v[114:115], v[146:147], v[146:147] op_sel:[0,1] op_sel_hi:[1,0]
	v_pk_add_f32 v[148:149], v[124:125], v[124:125] op_sel:[0,1] op_sel_hi:[1,0]
	v_pk_mul_f32 v[150:151], v[146:147], v[146:147]
	v_pk_mul_f32 v[152:153], v[124:125], v[124:125]
	v_pk_mul_f32 v[162:163], v[126:127], v[126:127]
	v_mul_f32_e32 v164, v122, v122
	v_mov_b32_e32 v182, v126
	v_mov_b32_e32 v184, v122
	v_pk_fma_f32 v[164:165], v[122:123], v[122:123], v[164:165] op_sel_hi:[1,1,0]
	v_mov_b32_e32 v183, v150
	v_mov_b32_e32 v150, v127
	v_mov_b32_e32 v185, v152
	v_mov_b32_e32 v152, v123
	v_mov_b32_e32 v115, v162
	v_mov_b32_e32 v149, v163
	v_pk_add_f32 v[150:151], v[182:183], v[150:151]
	v_pk_add_f32 v[152:153], v[184:185], v[152:153]
	v_pk_add_f32 v[114:115], v[114:115], v[148:149]
	v_mov_b32_e32 v164, v141
	v_pk_mul_f32 v[166:167], v[120:121], v[120:121]
	v_pk_mul_f32 v[168:169], v[116:117], v[116:117]
	v_pk_add_f32 v[150:151], v[150:151], v[152:153]
	v_pk_add_f32 v[114:115], v[114:115], v[164:165]
	v_mov_b32_e32 v188, v120
	v_mov_b32_e32 v189, v166
	v_mov_b32_e32 v166, v121
	v_pk_add_f32 v[114:115], v[150:151], v[114:115]
	v_mov_b32_e32 v150, v116
	v_mov_b32_e32 v151, v168
	v_mov_b32_e32 v168, v117
	v_pk_add_f32 v[148:149], v[188:189], v[166:167]
	v_pk_add_f32 v[150:151], v[150:151], v[168:169]
	v_pk_mul_f32 v[170:171], v[118:119], v[118:119]
	v_pk_mul_f32 v[174:175], v[112:113], v[112:113]
	v_pk_add_f32 v[148:149], v[148:149], v[150:151]
	v_mov_b32_e32 v150, v112
	v_pk_add_f32 v[114:115], v[114:115], v[148:149]
	v_mov_b32_e32 v148, v118
	v_mov_b32_e32 v149, v170
	v_mov_b32_e32 v170, v119
	v_mov_b32_e32 v151, v174
	v_mov_b32_e32 v174, v113
	v_pk_add_f32 v[148:149], v[148:149], v[170:171]
	v_pk_add_f32 v[150:151], v[150:151], v[174:175]
	s_lshl_b32 s7, s11, 3
	v_pk_add_f32 v[148:149], v[148:149], v[150:151]
	s_add_i32 s7, s7, 0
	v_pk_add_f32 v[114:115], v[114:115], v[148:149]
	ds_bpermute_b32 v148, v181, v114
	ds_bpermute_b32 v149, v181, v115
	v_lshlrev_b32_e32 v168, 16, v156
	v_and_b32_e32 v169, 0xffff0000, v156
	v_lshlrev_b32_e32 v156, 16, v157
	v_and_b32_e32 v157, 0xffff0000, v157
	s_waitcnt lgkmcnt(0)
; #define PG8_LAS __attribute__((address_space(3)))
;     __device__ __forceinline__ void fused(f32x4 (&acc)[2][2][4][2], const Unit& u, int wr, int wc, int fr, int fq, PG8_LAS unsigned char* lds, int wid, int lane) const {
;     ...
;         for (int ai = 0; ai < 2; ++ai)
; #pragma unroll
;             for (int m = 0; m < 4; ++m) {
;                 const int rl = ai * 128 + wr * 64 + m * 16 + fr;
;                 const size_t roff = (size_t)(u.pm * 256 + rl) * 1024 + u.pn * 256 + wc * 32 + fq * 8;
;                 float s1 = 0.f, s2 = 0.f;
; #pragma unroll
;                 for (int bj = 0; bj < 2; ++bj) {
;                     float x[8];
;                     if (RES_BF16) ld8f((const bfu*)res + roff + bj * 128, x);
;                     else ld8f32((const float*)res + roff + bj * 128, x);
; #pragma unroll
;                     for (int n = 0; n < 2; ++n) {
;                         f32x4 v = acc[ai][bj][m][n];
;                         v[0] += ALPHA * x[4 * n]; v[1] += ALPHA * x[4 * n + 1]; v[2] += ALPHA * x[4 * n + 2]; v[3] += ALPHA * x[4 * n + 3];
;                         acc[ai][bj][m][n] = v;
;                         s1 += (v[0] + v[1]) + (v[2] + v[3]); s2 += (v[0] * v[0] + v[1] * v[1]) + (v[2] * v[2] + v[3] * v[3]);
;                     }
;                 }
;                 s1 += __shfl_xor(s1, 16); s1 += __shfl_xor(s1, 32); s2 += __shfl_xor(s2, 16); s2 += __shfl_xor(s2, 32);
;                 {
;                     PG8_LAS float* pd = (fq == 0) ? P + (rl * 4 + wc) * 2 : (PG8_LAS float*)(lds + 12288) + tid * 2;
;                     pd[0] = s1; pd[1] = s2;
;                 }
	v_pk_add_f32 v[162:163], v[114:115], v[148:149]
	v_add_u32_e32 v148, s19, v179
	v_ashrrev_i32_e32 v149, 31, v148
	v_lshlrev_b64 v[148:149], 11, v[148:149]
	v_lshl_add_u64 v[150:151], s[28:29], 0, v[148:149]
	v_lshl_add_u64 v[150:151], v[150:151], 0, s[26:27]
	v_lshl_add_u64 v[150:151], v[150:151], 0, s[24:25]
	v_lshl_add_u64 v[166:167], v[150:151], 0, v[140:141]
	v_mov_b64_e32 v[150:151], v[218:219]
	v_mov_b64_e32 v[152:153], v[220:221]
	v_lshlrev_b32_e32 v114, 16, v154
	v_and_b32_e32 v115, 0xffff0000, v154
	v_lshlrev_b32_e32 v154, 16, v155
	v_and_b32_e32 v155, 0xffff0000, v155
	v_pk_fma_f32 v[114:115], v[114:115], s[6:7], v[108:109] op_sel_hi:[1,0,1]
	v_pk_fma_f32 v[108:109], v[154:155], s[6:7], v[110:111] op_sel_hi:[1,0,1]
	v_pk_fma_f32 v[106:107], v[156:157], s[6:7], v[106:107] op_sel_hi:[1,0,1]
	v_mov_b64_e32 v[154:155], v[222:223]
	v_mov_b64_e32 v[156:157], v[224:225]
	v_pk_fma_f32 v[110:111], v[168:169], s[6:7], v[104:105] op_sel_hi:[1,0,1]
	v_mul_f32_e32 v104, v106, v106
	v_pk_fma_f32 v[190:191], v[106:107], v[106:107], v[104:105] op_sel_hi:[1,1,0]
	v_lshlrev_b32_e32 v104, 16, v158
	v_and_b32_e32 v105, 0xffff0000, v158
	v_pk_add_f32 v[170:171], v[114:115], v[114:115] op_sel:[0,1] op_sel_hi:[1,0]
	v_pk_add_f32 v[174:175], v[108:109], v[108:109] op_sel:[0,1] op_sel_hi:[1,0]
	v_pk_mul_f32 v[168:169], v[110:111], v[110:111]
	v_lshlrev_b32_e32 v158, 16, v159
	v_and_b32_e32 v159, 0xffff0000, v159
	v_pk_fma_f32 v[100:101], v[104:105], s[6:7], v[100:101] op_sel_hi:[1,0,1]
	v_pk_fma_f32 v[102:103], v[158:159], s[6:7], v[102:103] op_sel_hi:[1,0,1]
	v_pk_mul_f32 v[158:159], v[100:101], v[100:101]
	v_mov_b32_e32 v171, v168
	v_mov_b32_e32 v175, v169
	v_pk_mul_f32 v[184:185], v[114:115], v[114:115]
	v_lshlrev_b32_e32 v192, 16, v160
	v_and_b32_e32 v193, 0xffff0000, v160
	v_pk_mul_f32 v[166:167], v[102:103], v[102:103]
	v_pk_add_f32 v[168:169], v[170:171], v[174:175]
	v_mov_b32_e32 v170, v100
	v_mov_b32_e32 v171, v158
	v_mov_b32_e32 v158, v101
	v_pk_mul_f32 v[188:189], v[108:109], v[108:109]
	v_lshlrev_b32_e32 v160, 16, v161
	v_and_b32_e32 v161, 0xffff0000, v161
	v_pk_fma_f32 v[104:105], v[192:193], s[6:7], v[96:97] op_sel_hi:[1,0,1]
	v_mov_b32_e32 v192, v110
	v_mov_b32_e32 v193, v184
	v_mov_b32_e32 v184, v111
	v_pk_add_f32 v[158:159], v[170:171], v[158:159]
	v_mov_b32_e32 v170, v102
	v_mov_b32_e32 v171, v166
	v_mov_b32_e32 v166, v103
	v_pk_fma_f32 v[96:97], v[160:161], s[6:7], v[98:99] op_sel_hi:[1,0,1]
	v_pk_mul_f32 v[98:99], v[104:105], v[104:105]
	v_pk_add_f32 v[184:185], v[192:193], v[184:185]
	v_mov_b32_e32 v192, v106
	v_mov_b32_e32 v193, v188
	v_mov_b32_e32 v188, v107
	v_pk_add_f32 v[166:167], v[170:171], v[166:167]
	v_pk_mul_f32 v[160:161], v[96:97], v[96:97]
	v_pk_add_f32 v[188:189], v[192:193], v[188:189]
	v_mov_b32_e32 v190, v141
	v_pk_add_f32 v[158:159], v[158:159], v[166:167]
	v_mov_b32_e32 v166, v104
	v_mov_b32_e32 v167, v98
	v_mov_b32_e32 v98, v105
	v_pk_add_f32 v[184:185], v[184:185], v[188:189]
	v_pk_add_f32 v[168:169], v[168:169], v[190:191]
	v_pk_add_f32 v[98:99], v[166:167], v[98:99]
	v_mov_b32_e32 v166, v96
	v_mov_b32_e32 v167, v160
	v_mov_b32_e32 v160, v97
	v_pk_add_f32 v[168:169], v[184:185], v[168:169]
	v_pk_add_f32 v[160:161], v[166:167], v[160:161]
	v_pk_add_f32 v[158:159], v[168:169], v[158:159]
	v_pk_add_f32 v[98:99], v[98:99], v[160:161]
	ds_bpermute_b32 v164, v180, v162
	v_pk_add_f32 v[98:99], v[158:159], v[98:99]
	ds_bpermute_b32 v165, v180, v163
	ds_bpermute_b32 v158, v181, v98
	ds_bpermute_b32 v159, v181, v99
	v_or_b32_e32 v182, 48, v129
	v_add_u32_e32 v183, 0x3000, v177
	s_waitcnt lgkmcnt(2)
	v_pk_add_f32 v[162:163], v[162:163], v[164:165]
	v_lshl_add_u32 v160, v129, 5, s7
	s_waitcnt lgkmcnt(0)
	v_pk_add_f32 v[164:165], v[98:99], v[158:159]
	v_add_u32_e32 v98, s19, v182
	v_ashrrev_i32_e32 v99, 31, v98
	v_lshlrev_b64 v[98:99], 11, v[98:99]
	v_lshl_add_u64 v[158:159], s[28:29], 0, v[98:99]
	v_lshl_add_u64 v[158:159], v[158:159], 0, s[26:27]
	v_lshl_add_u64 v[158:159], v[158:159], 0, s[24:25]
	v_lshl_add_u64 v[170:171], v[158:159], 0, v[140:141]
	v_cndmask_b32_e32 v200, v183, v160, vcc
	v_mov_b64_e32 v[158:159], v[226:227]
	v_mov_b64_e32 v[160:161], v[228:229]
	s_waitcnt vmcnt(2)
	v_lshlrev_b32_e32 v184, 16, v152
	v_and_b32_e32 v185, 0xffff0000, v152
	v_lshlrev_b32_e32 v152, 16, v153
	v_and_b32_e32 v153, 0xffff0000, v153
	v_lshlrev_b32_e32 v168, 16, v150
	v_and_b32_e32 v169, 0xffff0000, v150
	v_lshlrev_b32_e32 v174, 16, v151
	v_and_b32_e32 v175, 0xffff0000, v151
	v_pk_fma_f32 v[90:91], v[152:153], s[6:7], v[90:91] op_sel_hi:[1,0,1]
	v_pk_fma_f32 v[150:151], v[168:169], s[6:7], v[92:93] op_sel_hi:[1,0,1]
	v_pk_fma_f32 v[92:93], v[174:175], s[6:7], v[94:95] op_sel_hi:[1,0,1]
	v_pk_fma_f32 v[94:95], v[184:185], s[6:7], v[88:89] op_sel_hi:[1,0,1]
	v_mul_f32_e32 v88, v90, v90
	v_pk_fma_f32 v[184:185], v[90:91], v[90:91], v[88:89] op_sel_hi:[1,1,0]
	s_waitcnt vmcnt(1)
; #define PG8_LAS __attribute__((address_space(3)))
;     __device__ __forceinline__ void fused(f32x4 (&acc)[2][2][4][2], const Unit& u, int wr, int wc, int fr, int fq, PG8_LAS unsigned char* lds, int wid, int lane) const {
;     ...
;         for (int ai = 0; ai < 2; ++ai)
; #pragma unroll
;             for (int m = 0; m < 4; ++m) {
;                 const int rl = ai * 128 + wr * 64 + m * 16 + fr;
;                 const size_t roff = (size_t)(u.pm * 256 + rl) * 1024 + u.pn * 256 + wc * 32 + fq * 8;
;                 float s1 = 0.f, s2 = 0.f;
; #pragma unroll
;                 for (int bj = 0; bj < 2; ++bj) {
;                     float x[8];
;                     if (RES_BF16) ld8f((const bfu*)res + roff + bj * 128, x);
;                     else ld8f32((const float*)res + roff + bj * 128, x);
; #pragma unroll
;                     for (int n = 0; n < 2; ++n) {
;                         f32x4 v = acc[ai][bj][m][n];
;                         v[0] += ALPHA * x[4 * n]; v[1] += ALPHA * x[4 * n + 1]; v[2] += ALPHA * x[4 * n + 2]; v[3] += ALPHA * x[4 * n + 3];
;                         acc[ai][bj][m][n] = v;
;                         s1 += (v[0] + v[1]) + (v[2] + v[3]); s2 += (v[0] * v[0] + v[1] * v[1]) + (v[2] * v[2] + v[3] * v[3]);
;                     }
;                 }
;                 s1 += __shfl_xor(s1, 16); s1 += __shfl_xor(s1, 32); s2 += __shfl_xor(s2, 16); s2 += __shfl_xor(s2, 32);
;                 {
;                     PG8_LAS float* pd = (fq == 0) ? P + (rl * 4 + wc) * 2 : (PG8_LAS float*)(lds + 12288) + tid * 2;
;                     pd[0] = s1; pd[1] = s2;
;                 }
	v_lshlrev_b32_e32 v88, 16, v154
	v_and_b32_e32 v89, 0xffff0000, v154
	v_lshlrev_b32_e32 v192, 16, v155
	v_and_b32_e32 v193, 0xffff0000, v155
	v_lshlrev_b32_e32 v196, 16, v156
	v_and_b32_e32 v197, 0xffff0000, v156
	v_lshlrev_b32_e32 v198, 16, v157
	v_and_b32_e32 v199, 0xffff0000, v157
	v_mov_b64_e32 v[154:155], v[230:231]
	v_mov_b64_e32 v[156:157], v[232:233]
	v_pk_add_f32 v[168:169], v[150:151], v[150:151] op_sel:[0,1] op_sel_hi:[1,0]
	v_pk_add_f32 v[174:175], v[92:93], v[92:93] op_sel:[0,1] op_sel_hi:[1,0]
	v_pk_mul_f32 v[188:189], v[150:151], v[150:151]
	v_pk_mul_f32 v[152:153], v[94:95], v[94:95]
	v_pk_fma_f32 v[84:85], v[88:89], s[6:7], v[84:85] op_sel_hi:[1,0,1]
	v_pk_mul_f32 v[190:191], v[92:93], v[92:93]
	v_pk_fma_f32 v[86:87], v[192:193], s[6:7], v[86:87] op_sel_hi:[1,0,1]
	v_pk_mul_f32 v[170:171], v[84:85], v[84:85]
	v_pk_fma_f32 v[88:89], v[196:197], s[6:7], v[80:81] op_sel_hi:[1,0,1]
	v_pk_fma_f32 v[80:81], v[198:199], s[6:7], v[82:83] op_sel_hi:[1,0,1]
	v_mov_b32_e32 v198, v94
	v_mov_b32_e32 v199, v188
	v_mov_b32_e32 v188, v95
	v_mov_b32_e32 v169, v152
	v_mov_b32_e32 v175, v153
	v_pk_mul_f32 v[192:193], v[86:87], v[86:87]
	v_pk_add_f32 v[188:189], v[198:199], v[188:189]
	v_mov_b32_e32 v198, v90
	v_mov_b32_e32 v199, v190
	v_mov_b32_e32 v190, v91
	v_pk_add_f32 v[152:153], v[168:169], v[174:175]
	v_mov_b32_e32 v168, v84
	v_mov_b32_e32 v169, v170
	v_mov_b32_e32 v170, v85
	v_pk_add_f32 v[190:191], v[198:199], v[190:191]
	v_mov_b32_e32 v184, v141
	v_pk_add_f32 v[168:169], v[168:169], v[170:171]
	v_mov_b32_e32 v170, v86
	v_mov_b32_e32 v171, v192
	v_mov_b32_e32 v192, v87
	v_pk_add_f32 v[188:189], v[188:189], v[190:191]
	v_pk_add_f32 v[152:153], v[152:153], v[184:185]
	v_pk_add_f32 v[170:171], v[170:171], v[192:193]
	v_pk_mul_f32 v[82:83], v[88:89], v[88:89]
	v_pk_add_f32 v[152:153], v[188:189], v[152:153]
	v_pk_add_f32 v[168:169], v[168:169], v[170:171]
	v_pk_mul_f32 v[196:197], v[80:81], v[80:81]
	v_pk_add_f32 v[152:153], v[152:153], v[168:169]
	v_mov_b32_e32 v168, v88
	v_mov_b32_e32 v169, v82
	v_mov_b32_e32 v82, v89
	v_pk_add_f32 v[82:83], v[168:169], v[82:83]
	v_mov_b32_e32 v168, v80
	v_mov_b32_e32 v169, v196
	v_mov_b32_e32 v196, v81
	v_pk_add_f32 v[168:169], v[168:169], v[196:197]
	v_add_u32_e32 v188, 0x80, v129
	v_pk_add_f32 v[82:83], v[82:83], v[168:169]
	ds_bpermute_b32 v166, v180, v164
	v_pk_add_f32 v[82:83], v[152:153], v[82:83]
	ds_bpermute_b32 v152, v181, v82
	ds_bpermute_b32 v153, v181, v83
	ds_bpermute_b32 v167, v180, v165
	ds_write_b64 v200, v[162:163]
	v_lshl_add_u32 v162, v178, 5, s7
	v_cndmask_b32_e32 v189, v183, v162, vcc
	s_waitcnt lgkmcnt(2)
	v_pk_add_f32 v[168:169], v[82:83], v[152:153]
	v_add_u32_e32 v82, s19, v188
	v_ashrrev_i32_e32 v83, 31, v82
	s_waitcnt vmcnt(1)
	v_lshlrev_b32_e32 v184, 16, v160
	v_and_b32_e32 v185, 0xffff0000, v160
	v_lshlrev_b32_e32 v160, 16, v161
	v_and_b32_e32 v161, 0xffff0000, v161
	v_lshlrev_b32_e32 v152, 16, v158
	v_lshlrev_b64 v[82:83], 11, v[82:83]
	v_and_b32_e32 v153, 0xffff0000, v158
	v_lshlrev_b32_e32 v158, 16, v159
	v_and_b32_e32 v159, 0xffff0000, v159
	v_pk_fma_f32 v[74:75], v[160:161], s[6:7], v[74:75] op_sel_hi:[1,0,1]
	v_lshl_add_u64 v[162:163], s[28:29], 0, v[82:83]
	v_pk_fma_f32 v[152:153], v[152:153], s[6:7], v[76:77] op_sel_hi:[1,0,1]
	v_pk_fma_f32 v[76:77], v[158:159], s[6:7], v[78:79] op_sel_hi:[1,0,1]
	v_pk_fma_f32 v[78:79], v[184:185], s[6:7], v[72:73] op_sel_hi:[1,0,1]
	v_mul_f32_e32 v72, v74, v74
	v_lshl_add_u64 v[162:163], v[162:163], 0, s[26:27]
	v_pk_add_f32 v[190:191], v[152:153], v[152:153] op_sel:[0,1] op_sel_hi:[1,0]
	v_pk_add_f32 v[192:193], v[76:77], v[76:77] op_sel:[0,1] op_sel_hi:[1,0]
	v_pk_mul_f32 v[160:161], v[78:79], v[78:79]
	v_pk_fma_f32 v[184:185], v[74:75], v[74:75], v[72:73] op_sel_hi:[1,1,0]
	s_waitcnt vmcnt(0)
	v_lshlrev_b32_e32 v72, 16, v154
	v_and_b32_e32 v73, 0xffff0000, v154
	v_lshl_add_u64 v[162:163], v[162:163], 0, s[24:25]
	v_pk_mul_f32 v[196:197], v[152:153], v[152:153]
	v_lshlrev_b32_e32 v154, 16, v155
	v_and_b32_e32 v155, 0xffff0000, v155
	v_lshlrev_b32_e32 v200, 16, v156
	v_and_b32_e32 v201, 0xffff0000, v156
	v_lshlrev_b32_e32 v202, 16, v157
	v_and_b32_e32 v203, 0xffff0000, v157
	v_pk_fma_f32 v[68:69], v[72:73], s[6:7], v[68:69] op_sel_hi:[1,0,1]
	v_mov_b32_e32 v191, v160
	v_mov_b32_e32 v193, v161
	v_lshl_add_u64 v[174:175], v[162:163], 0, v[140:141]
	v_pk_mul_f32 v[198:199], v[76:77], v[76:77]
	v_pk_fma_f32 v[70:71], v[154:155], s[6:7], v[70:71] op_sel_hi:[1,0,1]
	v_pk_mul_f32 v[154:155], v[68:69], v[68:69]
	v_pk_fma_f32 v[72:73], v[200:201], s[6:7], v[64:65] op_sel_hi:[1,0,1]
	v_pk_fma_f32 v[64:65], v[202:203], s[6:7], v[66:67] op_sel_hi:[1,0,1]
	v_mov_b32_e32 v202, v78
	v_mov_b32_e32 v203, v196
	v_mov_b32_e32 v196, v79
	v_pk_add_f32 v[160:161], v[190:191], v[192:193]
	v_mov_b32_e32 v184, v141
	s_waitcnt lgkmcnt(1)
	v_pk_add_f32 v[166:167], v[164:165], v[166:167]
	v_mov_b64_e32 v[162:163], v[234:235]
	v_mov_b64_e32 v[164:165], v[236:237]
	v_mov_b64_e32 v[156:157], v[238:239]
	v_mov_b64_e32 v[158:159], v[240:241]
	v_pk_mul_f32 v[174:175], v[70:71], v[70:71]
	v_pk_add_f32 v[196:197], v[202:203], v[196:197]
	v_mov_b32_e32 v202, v74
	v_mov_b32_e32 v203, v198
	v_mov_b32_e32 v198, v75
	v_pk_add_f32 v[160:161], v[160:161], v[184:185]
	v_mov_b32_e32 v184, v68
	v_mov_b32_e32 v185, v154
	v_mov_b32_e32 v154, v69
	v_pk_add_f32 v[198:199], v[202:203], v[198:199]
	v_pk_add_f32 v[154:155], v[184:185], v[154:155]
	v_mov_b32_e32 v184, v70
	v_mov_b32_e32 v185, v174
	v_mov_b32_e32 v174, v71
	v_pk_add_f32 v[196:197], v[196:197], v[198:199]
	v_pk_add_f32 v[174:175], v[184:185], v[174:175]
	v_pk_mul_f32 v[66:67], v[72:73], v[72:73]
	v_pk_add_f32 v[160:161], v[196:197], v[160:161]
	v_pk_add_f32 v[154:155], v[154:155], v[174:175]
	v_pk_mul_f32 v[200:201], v[64:65], v[64:65]
	v_pk_add_f32 v[154:155], v[160:161], v[154:155]
	v_mov_b32_e32 v160, v72
	v_mov_b32_e32 v161, v66
	v_mov_b32_e32 v66, v73
	v_pk_add_f32 v[66:67], v[160:161], v[66:67]
	v_mov_b32_e32 v160, v64
	v_mov_b32_e32 v161, v200
	v_mov_b32_e32 v200, v65
	v_pk_add_f32 v[160:161], v[160:161], v[200:201]
	ds_write_b64 v189, v[166:167]
	v_pk_add_f32 v[66:67], v[66:67], v[160:161]
	v_add_u32_e32 v189, 0x90, v129
	v_pk_add_f32 v[66:67], v[154:155], v[66:67]
	ds_bpermute_b32 v154, v181, v66
	ds_bpermute_b32 v155, v181, v67
	ds_bpermute_b32 v170, v180, v168
	ds_bpermute_b32 v171, v180, v169
	v_lshl_add_u32 v160, v179, 5, s7
	v_cndmask_b32_e32 v206, v183, v160, vcc
	s_waitcnt lgkmcnt(2)
; #define PG8_LAS __attribute__((address_space(3)))
;     __device__ __forceinline__ void fused(f32x4 (&acc)[2][2][4][2], const Unit& u, int wr, int wc, int fr, int fq, PG8_LAS unsigned char* lds, int wid, int lane) const {
;     ...
;         for (int ai = 0; ai < 2; ++ai)
; #pragma unroll
;             for (int m = 0; m < 4; ++m) {
;                 const int rl = ai * 128 + wr * 64 + m * 16 + fr;
;                 const size_t roff = (size_t)(u.pm * 256 + rl) * 1024 + u.pn * 256 + wc * 32 + fq * 8;
;                 float s1 = 0.f, s2 = 0.f;
; #pragma unroll
;                 for (int bj = 0; bj < 2; ++bj) {
;                     float x[8];
;                     if (RES_BF16) ld8f((const bfu*)res + roff + bj * 128, x);
;                     else ld8f32((const float*)res + roff + bj * 128, x);
; #pragma unroll
;                     for (int n = 0; n < 2; ++n) {
;                         f32x4 v = acc[ai][bj][m][n];
;                         v[0] += ALPHA * x[4 * n]; v[1] += ALPHA * x[4 * n + 1]; v[2] += ALPHA * x[4 * n + 2]; v[3] += ALPHA * x[4 * n + 3];
;                         acc[ai][bj][m][n] = v;
;                         s1 += (v[0] + v[1]) + (v[2] + v[3]); s2 += (v[0] * v[0] + v[1] * v[1]) + (v[2] * v[2] + v[3] * v[3]);
;                     }
;                 }
;                 s1 += __shfl_xor(s1, 16); s1 += __shfl_xor(s1, 32); s2 += __shfl_xor(s2, 16); s2 += __shfl_xor(s2, 32);
;                 {
;                     PG8_LAS float* pd = (fq == 0) ? P + (rl * 4 + wc) * 2 : (PG8_LAS float*)(lds + 12288) + tid * 2;
;                     pd[0] = s1; pd[1] = s2;
;                 }
	v_pk_add_f32 v[174:175], v[66:67], v[154:155]
	v_add_u32_e32 v66, s19, v189
	v_ashrrev_i32_e32 v67, 31, v66
	v_lshlrev_b64 v[66:67], 11, v[66:67]
	v_lshl_add_u64 v[160:161], s[28:29], 0, v[66:67]
	v_lshl_add_u64 v[160:161], v[160:161], 0, s[26:27]
	v_lshl_add_u64 v[160:161], v[160:161], 0, s[24:25]
	v_lshl_add_u64 v[160:161], v[160:161], 0, v[140:141]
	s_waitcnt lgkmcnt(0)
	v_pk_add_f32 v[170:171], v[168:169], v[170:171]
	v_mov_b64_e32 v[166:167], v[242:243]
	v_mov_b64_e32 v[168:169], v[244:245]
	ds_bpermute_b32 v184, v180, v174
	ds_bpermute_b32 v185, v180, v175
	ds_write_b64 v206, v[170:171]
	s_waitcnt lgkmcnt(1)
	v_pk_add_f32 v[170:171], v[174:175], v[184:185]
	s_waitcnt vmcnt(2)
	v_lshlrev_b32_e32 v190, 16, v164
	v_and_b32_e32 v191, 0xffff0000, v164
	v_lshlrev_b32_e32 v164, 16, v165
	v_and_b32_e32 v165, 0xffff0000, v165
	v_lshlrev_b32_e32 v154, 16, v162
	v_and_b32_e32 v155, 0xffff0000, v162
	v_lshlrev_b32_e32 v162, 16, v163
	v_and_b32_e32 v163, 0xffff0000, v163
	v_pk_fma_f32 v[58:59], v[164:165], s[6:7], v[58:59] op_sel_hi:[1,0,1]
	v_pk_fma_f32 v[154:155], v[154:155], s[6:7], v[60:61] op_sel_hi:[1,0,1]
	v_pk_fma_f32 v[60:61], v[162:163], s[6:7], v[62:63] op_sel_hi:[1,0,1]
	v_pk_fma_f32 v[62:63], v[190:191], s[6:7], v[56:57] op_sel_hi:[1,0,1]
	v_mul_f32_e32 v56, v58, v58
	v_pk_fma_f32 v[190:191], v[58:59], v[58:59], v[56:57] op_sel_hi:[1,1,0]
	s_waitcnt vmcnt(1)
	v_lshlrev_b32_e32 v56, 16, v156
	v_and_b32_e32 v57, 0xffff0000, v156
	v_lshlrev_b32_e32 v200, 16, v158
	v_and_b32_e32 v201, 0xffff0000, v158
	v_lshlrev_b32_e32 v202, 16, v159
	v_and_b32_e32 v203, 0xffff0000, v159
	v_mov_b64_e32 v[158:159], v[246:247]
	v_mov_b64_e32 v[160:161], v[248:249]
	v_pk_mul_f32 v[196:197], v[154:155], v[154:155]
	v_lshlrev_b32_e32 v156, 16, v157
	v_and_b32_e32 v157, 0xffff0000, v157
	v_pk_fma_f32 v[52:53], v[56:57], s[6:7], v[52:53] op_sel_hi:[1,0,1]
	v_pk_add_f32 v[162:163], v[154:155], v[154:155] op_sel:[0,1] op_sel_hi:[1,0]
	v_pk_add_f32 v[192:193], v[60:61], v[60:61] op_sel:[0,1] op_sel_hi:[1,0]
	v_pk_mul_f32 v[198:199], v[60:61], v[60:61]
	v_pk_mul_f32 v[164:165], v[62:63], v[62:63]
	v_pk_fma_f32 v[54:55], v[156:157], s[6:7], v[54:55] op_sel_hi:[1,0,1]
	v_pk_mul_f32 v[156:157], v[52:53], v[52:53]
	v_pk_fma_f32 v[56:57], v[200:201], s[6:7], v[48:49] op_sel_hi:[1,0,1]
	v_pk_fma_f32 v[48:49], v[202:203], s[6:7], v[50:51] op_sel_hi:[1,0,1]
	v_mov_b32_e32 v202, v62
	v_mov_b32_e32 v203, v196
	v_mov_b32_e32 v196, v63
	v_pk_mul_f32 v[204:205], v[54:55], v[54:55]
	v_pk_add_f32 v[196:197], v[202:203], v[196:197]
	v_mov_b32_e32 v202, v58
	v_mov_b32_e32 v203, v198
	v_mov_b32_e32 v198, v59
	v_mov_b32_e32 v163, v164
	v_mov_b32_e32 v193, v165
	v_mov_b32_e32 v164, v52
	v_mov_b32_e32 v165, v156
	v_mov_b32_e32 v156, v53
	v_pk_add_f32 v[198:199], v[202:203], v[198:199]
	v_pk_add_f32 v[162:163], v[162:163], v[192:193]
	v_mov_b32_e32 v190, v141
	v_pk_add_f32 v[156:157], v[164:165], v[156:157]
	v_mov_b32_e32 v164, v54
	v_mov_b32_e32 v165, v204
	v_mov_b32_e32 v204, v55
	v_pk_add_f32 v[196:197], v[196:197], v[198:199]
	v_pk_add_f32 v[162:163], v[162:163], v[190:191]
	v_pk_add_f32 v[164:165], v[164:165], v[204:205]
	v_pk_mul_f32 v[50:51], v[56:57], v[56:57]
	v_pk_add_f32 v[162:163], v[196:197], v[162:163]
	v_pk_add_f32 v[156:157], v[156:157], v[164:165]
	v_pk_mul_f32 v[200:201], v[48:49], v[48:49]
	v_pk_add_f32 v[156:157], v[162:163], v[156:157]
	v_mov_b32_e32 v162, v56
	v_mov_b32_e32 v163, v50
	v_mov_b32_e32 v50, v57
	v_pk_add_f32 v[50:51], v[162:163], v[50:51]
	v_mov_b32_e32 v162, v48
	v_mov_b32_e32 v163, v200
	v_mov_b32_e32 v200, v49
	v_pk_add_f32 v[162:163], v[162:163], v[200:201]
	v_add_u32_e32 v190, 0xa0, v129
	v_pk_add_f32 v[50:51], v[50:51], v[162:163]
	v_lshl_add_u32 v162, v182, 5, s7
	v_pk_add_f32 v[50:51], v[156:157], v[50:51]
	ds_bpermute_b32 v156, v181, v50
	ds_bpermute_b32 v157, v181, v51
	v_cndmask_b32_e32 v191, v183, v162, vcc
	s_waitcnt vmcnt(1)
	v_lshlrev_b32_e32 v162, 16, v168
	v_and_b32_e32 v163, 0xffff0000, v168
	ds_write_b64 v191, v[170:171]
	s_waitcnt lgkmcnt(1)
	v_pk_add_f32 v[174:175], v[50:51], v[156:157]
	v_lshlrev_b32_e32 v50, 16, v166
	v_and_b32_e32 v51, 0xffff0000, v166
	v_lshlrev_b32_e32 v156, 16, v167
	v_and_b32_e32 v157, 0xffff0000, v167
	v_pk_fma_f32 v[50:51], v[50:51], s[6:7], v[44:45] op_sel_hi:[1,0,1]
	v_pk_fma_f32 v[44:45], v[156:157], s[6:7], v[46:47] op_sel_hi:[1,0,1]
	v_pk_fma_f32 v[46:47], v[162:163], s[6:7], v[40:41] op_sel_hi:[1,0,1]
	v_add_u32_e32 v40, s19, v190
	v_ashrrev_i32_e32 v41, 31, v40
	v_lshlrev_b64 v[156:157], 11, v[40:41]
	v_lshl_add_u64 v[40:41], s[28:29], 0, v[156:157]
	v_lshl_add_u64 v[40:41], v[40:41], 0, s[26:27]
	v_lshl_add_u64 v[40:41], v[40:41], 0, s[24:25]
	v_lshlrev_b32_e32 v166, 16, v169
	v_and_b32_e32 v167, 0xffff0000, v169
	v_lshl_add_u64 v[168:169], v[40:41], 0, v[140:141]
	global_load_dwordx4 v[162:165], v[168:169], off
	v_pk_fma_f32 v[42:43], v[166:167], s[6:7], v[42:43] op_sel_hi:[1,0,1]
	v_pk_add_f32 v[192:193], v[50:51], v[50:51] op_sel:[0,1] op_sel_hi:[1,0]
	v_mul_f32_e32 v40, v42, v42
	v_pk_fma_f32 v[204:205], v[42:43], v[42:43], v[40:41] op_sel_hi:[1,1,0]
	s_waitcnt vmcnt(1)
; #define PG8_LAS __attribute__((address_space(3)))
;     __device__ __forceinline__ void fused(f32x4 (&acc)[2][2][4][2], const Unit& u, int wr, int wc, int fr, int fq, PG8_LAS unsigned char* lds, int wid, int lane) const {
;     ...
;         for (int ai = 0; ai < 2; ++ai)
; #pragma unroll
;             for (int m = 0; m < 4; ++m) {
;                 const int rl = ai * 128 + wr * 64 + m * 16 + fr;
;                 const size_t roff = (size_t)(u.pm * 256 + rl) * 1024 + u.pn * 256 + wc * 32 + fq * 8;
;                 float s1 = 0.f, s2 = 0.f;
; #pragma unroll
;                 for (int bj = 0; bj < 2; ++bj) {
;                     float x[8];
;                     if (RES_BF16) ld8f((const bfu*)res + roff + bj * 128, x);
;                     else ld8f32((const float*)res + roff + bj * 128, x);
; #pragma unroll
;                     for (int n = 0; n < 2; ++n) {
;                         f32x4 v = acc[ai][bj][m][n];
;                         v[0] += ALPHA * x[4 * n]; v[1] += ALPHA * x[4 * n + 1]; v[2] += ALPHA * x[4 * n + 2]; v[3] += ALPHA * x[4 * n + 3];
;                         acc[ai][bj][m][n] = v;
;                         s1 += (v[0] + v[1]) + (v[2] + v[3]); s2 += (v[0] * v[0] + v[1] * v[1]) + (v[2] * v[2] + v[3] * v[3]);
;                     }
;                 }
;                 s1 += __shfl_xor(s1, 16); s1 += __shfl_xor(s1, 32); s2 += __shfl_xor(s2, 16); s2 += __shfl_xor(s2, 32);
;                 {
;                     PG8_LAS float* pd = (fq == 0) ? P + (rl * 4 + wc) * 2 : (PG8_LAS float*)(lds + 12288) + tid * 2;
;                     pd[0] = s1; pd[1] = s2;
;                 }
	v_lshlrev_b32_e32 v40, 16, v158
	v_and_b32_e32 v41, 0xffff0000, v158
	v_pk_add_f32 v[196:197], v[44:45], v[44:45] op_sel:[0,1] op_sel_hi:[1,0]
	v_pk_mul_f32 v[198:199], v[50:51], v[50:51]
	v_pk_mul_f32 v[202:203], v[46:47], v[46:47]
	v_lshlrev_b32_e32 v158, 16, v159
	v_and_b32_e32 v159, 0xffff0000, v159
	v_pk_fma_f32 v[40:41], v[40:41], s[6:7], v[36:37] op_sel_hi:[1,0,1]
	v_pk_mul_f32 v[200:201], v[44:45], v[44:45]
	v_pk_fma_f32 v[36:37], v[158:159], s[6:7], v[38:39] op_sel_hi:[1,0,1]
	v_pk_mul_f32 v[158:159], v[40:41], v[40:41]
	v_mov_b32_e32 v208, v46
	v_mov_b32_e32 v209, v198
	v_mov_b32_e32 v198, v47
	v_mov_b32_e32 v193, v202
	v_mov_b32_e32 v197, v203
	v_pk_mul_f32 v[206:207], v[36:37], v[36:37]
	v_pk_add_f32 v[198:199], v[208:209], v[198:199]
	v_mov_b32_e32 v208, v42
	v_mov_b32_e32 v209, v200
	v_mov_b32_e32 v200, v43
	v_pk_add_f32 v[192:193], v[192:193], v[196:197]
	v_mov_b32_e32 v196, v40
	v_mov_b32_e32 v197, v158
	v_mov_b32_e32 v158, v41
	v_lshlrev_b32_e32 v166, 16, v160
	v_and_b32_e32 v167, 0xffff0000, v160
	v_pk_add_f32 v[200:201], v[208:209], v[200:201]
	v_mov_b32_e32 v204, v141
	v_pk_add_f32 v[158:159], v[196:197], v[158:159]
	v_mov_b32_e32 v196, v36
	v_mov_b32_e32 v197, v206
	v_mov_b32_e32 v206, v37
	v_lshlrev_b32_e32 v160, 16, v161
	v_and_b32_e32 v161, 0xffff0000, v161
	v_pk_fma_f32 v[38:39], v[166:167], s[6:7], v[32:33] op_sel_hi:[1,0,1]
	v_pk_add_f32 v[198:199], v[198:199], v[200:201]
	v_pk_add_f32 v[192:193], v[192:193], v[204:205]
	v_pk_add_f32 v[196:197], v[196:197], v[206:207]
	v_pk_fma_f32 v[32:33], v[160:161], s[6:7], v[34:35] op_sel_hi:[1,0,1]
	v_pk_mul_f32 v[34:35], v[38:39], v[38:39]
	v_pk_add_f32 v[192:193], v[198:199], v[192:193]
	v_pk_add_f32 v[158:159], v[158:159], v[196:197]
	v_pk_mul_f32 v[160:161], v[32:33], v[32:33]
	v_pk_add_f32 v[158:159], v[192:193], v[158:159]
	v_mov_b32_e32 v192, v38
	v_mov_b32_e32 v193, v34
	v_mov_b32_e32 v34, v39
	v_pk_add_f32 v[34:35], v[192:193], v[34:35]
	v_mov_b32_e32 v192, v32
	v_mov_b32_e32 v193, v160
	v_mov_b32_e32 v160, v33
	v_pk_add_f32 v[160:161], v[192:193], v[160:161]
	global_load_dwordx4 v[166:169], v[168:169], off offset:256
	v_pk_add_f32 v[34:35], v[34:35], v[160:161]
	ds_bpermute_b32 v184, v180, v174
	v_pk_add_f32 v[34:35], v[158:159], v[34:35]
	ds_bpermute_b32 v158, v181, v34
	ds_bpermute_b32 v159, v181, v35
	ds_bpermute_b32 v185, v180, v175
	v_add_u32_e32 v191, 0xb0, v129
	v_lshl_add_u32 v160, v188, 5, s7
	v_cndmask_b32_e32 v192, v183, v160, vcc
	s_waitcnt lgkmcnt(1)
	v_pk_add_f32 v[158:159], v[34:35], v[158:159]
	v_add_u32_e32 v34, s19, v191
	v_ashrrev_i32_e32 v35, 31, v34
	ds_bpermute_b32 v170, v180, v158
	ds_bpermute_b32 v171, v180, v159
	v_lshlrev_b64 v[34:35], 11, v[34:35]
	s_waitcnt lgkmcnt(2)
	v_pk_add_f32 v[160:161], v[174:175], v[184:185]
	v_lshl_add_u64 v[174:175], s[28:29], 0, v[34:35]
	v_lshl_add_u64 v[174:175], v[174:175], 0, s[26:27]
	v_lshl_add_u64 v[174:175], v[174:175], 0, s[24:25]
	v_lshl_add_u64 v[174:175], v[174:175], 0, v[140:141]
	v_lshl_add_u32 v140, v189, 5, s7
	global_load_dwordx4 v[196:199], v[174:175], off
	v_cndmask_b32_e32 v140, v183, v140, vcc
	s_waitcnt lgkmcnt(0)
	v_pk_add_f32 v[158:159], v[158:159], v[170:171]
	ds_write_b64 v192, v[160:161]
	ds_write_b64 v140, v[158:159]
	s_waitcnt vmcnt(2)
	v_lshlrev_b32_e32 v158, 16, v162
	v_and_b32_e32 v159, 0xffff0000, v162
	v_lshlrev_b32_e32 v162, 16, v163
	v_and_b32_e32 v163, 0xffff0000, v163
	v_pk_fma_f32 v[160:161], v[158:159], s[6:7], v[28:29] op_sel_hi:[1,0,1]
	v_pk_fma_f32 v[158:159], v[162:163], s[6:7], v[30:31] op_sel_hi:[1,0,1]
	global_load_dwordx4 v[28:31], v[174:175], off offset:256
	v_lshlrev_b32_e32 v184, 16, v165
	v_and_b32_e32 v185, 0xffff0000, v165
	v_lshlrev_b32_e32 v170, 16, v164
	v_and_b32_e32 v171, 0xffff0000, v164
	v_pk_fma_f32 v[162:163], v[184:185], s[6:7], v[26:27] op_sel_hi:[1,0,1]
	v_pk_fma_f32 v[164:165], v[170:171], s[6:7], v[24:25] op_sel_hi:[1,0,1]
	v_mul_f32_e32 v24, v162, v162
	v_pk_add_f32 v[192:193], v[160:161], v[160:161] op_sel:[0,1] op_sel_hi:[1,0]
	v_pk_add_f32 v[200:201], v[158:159], v[158:159] op_sel:[0,1] op_sel_hi:[1,0]
	v_pk_mul_f32 v[26:27], v[164:165], v[164:165]
	v_pk_fma_f32 v[170:171], v[162:163], v[162:163], v[24:25] op_sel_hi:[1,1,0]
	v_pk_mul_f32 v[202:203], v[160:161], v[160:161]
	v_mov_b32_e32 v193, v26
	v_mov_b32_e32 v201, v27
	v_pk_mul_f32 v[174:175], v[158:159], v[158:159]
	v_pk_add_f32 v[26:27], v[192:193], v[200:201]
	v_mov_b32_e32 v170, v141
	v_pk_add_f32 v[26:27], v[26:27], v[170:171]
	v_lshl_add_u32 v140, v190, 5, s7
	s_waitcnt vmcnt(2)
; #define PG8_LAS __attribute__((address_space(3)))
;     __device__ __forceinline__ void fused(f32x4 (&acc)[2][2][4][2], const Unit& u, int wr, int wc, int fr, int fq, PG8_LAS unsigned char* lds, int wid, int lane) const {
;     ...
;                         f32x4 v = acc[ai][bj][m][n];
;                         v[0] += ALPHA * x[4 * n]; v[1] += ALPHA * x[4 * n + 1]; v[2] += ALPHA * x[4 * n + 2]; v[3] += ALPHA * x[4 * n + 3];
;                         acc[ai][bj][m][n] = v;
;                         s1 += (v[0] + v[1]) + (v[2] + v[3]); s2 += (v[0] * v[0] + v[1] * v[1]) + (v[2] * v[2] + v[3] * v[3]);
;                     }
;                 }
;                 s1 += __shfl_xor(s1, 16); s1 += __shfl_xor(s1, 32); s2 += __shfl_xor(s2, 16); s2 += __shfl_xor(s2, 32);
;                 {
;                     PG8_LAS float* pd = (fq == 0) ? P + (rl * 4 + wc) * 2 : (PG8_LAS float*)(lds + 12288) + tid * 2;
;                     pd[0] = s1; pd[1] = s2;
;                 }
;             }
;         __syncthreads();
;         if (tid < 256) {
;             const float a = P[tid * 8] + P[tid * 8 + 2] + P[tid * 8 + 4] + P[tid * 8 + 6], b = P[tid * 8 + 1] + P[tid * 8 + 3] + P[tid * 8 + 5] + P[tid * 8 + 7];
;             const unsigned long long pk = (unsigned long long)__float_as_uint(a) | ((unsigned long long)__float_as_uint(b) << 32);
;             __hip_atomic_store(xch + ((size_t)(u.pm * 256 + tid) * 4 + u.pn), pk, __ATOMIC_RELAXED, __HIP_MEMORY_SCOPE_AGENT);
;         }
	v_lshlrev_b32_e32 v24, 16, v166
	v_and_b32_e32 v25, 0xffff0000, v166
	v_lshlrev_b32_e32 v166, 16, v167
	v_and_b32_e32 v167, 0xffff0000, v167
	v_lshlrev_b32_e32 v184, 16, v168
	v_and_b32_e32 v185, 0xffff0000, v168
	v_pk_fma_f32 v[24:25], v[24:25], s[6:7], v[20:21] op_sel_hi:[1,0,1]
	v_pk_fma_f32 v[20:21], v[166:167], s[6:7], v[22:23] op_sel_hi:[1,0,1]
	v_pk_mul_f32 v[166:167], v[24:25], v[24:25]
	v_pk_fma_f32 v[22:23], v[184:185], s[6:7], v[16:17] op_sel_hi:[1,0,1]
	v_mov_b32_e32 v184, v164
	v_mov_b32_e32 v185, v202
	v_mov_b32_e32 v202, v165
	v_pk_mul_f32 v[204:205], v[20:21], v[20:21]
	v_pk_add_f32 v[184:185], v[184:185], v[202:203]
	v_mov_b32_e32 v202, v162
	v_mov_b32_e32 v203, v174
	v_mov_b32_e32 v174, v163
	v_mov_b32_e32 v170, v24
	v_mov_b32_e32 v171, v166
	v_mov_b32_e32 v166, v25
	v_pk_add_f32 v[174:175], v[202:203], v[174:175]
	v_pk_add_f32 v[166:167], v[170:171], v[166:167]
	v_mov_b32_e32 v170, v20
	v_mov_b32_e32 v171, v204
	v_mov_b32_e32 v204, v21
	v_lshlrev_b32_e32 v168, 16, v169
	v_and_b32_e32 v169, 0xffff0000, v169
	v_pk_add_f32 v[174:175], v[184:185], v[174:175]
	v_pk_add_f32 v[170:171], v[170:171], v[204:205]
	v_pk_fma_f32 v[16:17], v[168:169], s[6:7], v[18:19] op_sel_hi:[1,0,1]
	v_pk_mul_f32 v[18:19], v[22:23], v[22:23]
	v_pk_add_f32 v[26:27], v[174:175], v[26:27]
	v_pk_add_f32 v[166:167], v[166:167], v[170:171]
	v_pk_mul_f32 v[168:169], v[16:17], v[16:17]
	v_pk_add_f32 v[26:27], v[26:27], v[166:167]
	v_mov_b32_e32 v166, v22
	v_mov_b32_e32 v167, v18
	v_mov_b32_e32 v18, v23
	v_pk_add_f32 v[18:19], v[166:167], v[18:19]
	v_mov_b32_e32 v166, v16
	v_mov_b32_e32 v167, v168
	v_mov_b32_e32 v168, v17
	v_pk_add_f32 v[166:167], v[166:167], v[168:169]
	s_waitcnt vmcnt(1)
	v_lshlrev_b32_e32 v168, 16, v198
	v_pk_add_f32 v[18:19], v[18:19], v[166:167]
	v_and_b32_e32 v169, 0xffff0000, v198
	v_pk_add_f32 v[184:185], v[26:27], v[18:19]
	v_lshlrev_b32_e32 v18, 16, v196
	v_and_b32_e32 v19, 0xffff0000, v196
	v_lshlrev_b32_e32 v26, 16, v197
	v_and_b32_e32 v27, 0xffff0000, v197
	v_lshlrev_b32_e32 v196, 16, v199
	v_and_b32_e32 v197, 0xffff0000, v199
	v_pk_fma_f32 v[170:171], v[18:19], s[6:7], v[12:13] op_sel_hi:[1,0,1]
	v_pk_fma_f32 v[166:167], v[26:27], s[6:7], v[14:15] op_sel_hi:[1,0,1]
	v_pk_fma_f32 v[174:175], v[168:169], s[6:7], v[8:9] op_sel_hi:[1,0,1]
	v_pk_fma_f32 v[168:169], v[196:197], s[6:7], v[10:11] op_sel_hi:[1,0,1]
	v_pk_add_f32 v[12:13], v[170:171], v[170:171] op_sel:[0,1] op_sel_hi:[1,0]
	v_pk_add_f32 v[14:15], v[166:167], v[166:167] op_sel:[0,1] op_sel_hi:[1,0]
	v_pk_mul_f32 v[8:9], v[174:175], v[174:175]
	v_mul_f32_e32 v10, v168, v168
	s_waitcnt vmcnt(0)
	v_lshlrev_b32_e32 v18, 16, v28
	v_and_b32_e32 v19, 0xffff0000, v28
	v_pk_fma_f32 v[10:11], v[168:169], v[168:169], v[10:11] op_sel_hi:[1,1,0]
	v_lshlrev_b32_e32 v28, 16, v29
	v_and_b32_e32 v29, 0xffff0000, v29
	v_pk_fma_f32 v[26:27], v[18:19], s[6:7], v[4:5] op_sel_hi:[1,0,1]
	v_mov_b32_e32 v13, v8
	v_mov_b32_e32 v15, v9
	v_pk_fma_f32 v[18:19], v[28:29], s[6:7], v[6:7] op_sel_hi:[1,0,1]
	v_pk_mul_f32 v[4:5], v[26:27], v[26:27]
	v_pk_add_f32 v[8:9], v[12:13], v[14:15]
	v_mov_b32_e32 v10, v141
	v_pk_mul_f32 v[198:199], v[170:171], v[170:171]
	v_lshlrev_b32_e32 v196, 16, v30
	v_and_b32_e32 v197, 0xffff0000, v30
	v_pk_mul_f32 v[6:7], v[18:19], v[18:19]
	v_pk_add_f32 v[8:9], v[8:9], v[10:11]
	v_mov_b32_e32 v10, v26
	v_mov_b32_e32 v11, v4
	v_mov_b32_e32 v4, v27
	v_pk_mul_f32 v[200:201], v[166:167], v[166:167]
	v_lshlrev_b32_e32 v202, 16, v31
	v_and_b32_e32 v203, 0xffff0000, v31
	v_pk_fma_f32 v[30:31], v[196:197], s[6:7], v[0:1] op_sel_hi:[1,0,1]
	v_mov_b32_e32 v196, v174
	v_mov_b32_e32 v197, v198
	v_mov_b32_e32 v198, v175
	v_pk_add_f32 v[4:5], v[10:11], v[4:5]
	v_mov_b32_e32 v10, v18
	v_mov_b32_e32 v11, v6
	v_mov_b32_e32 v6, v19
	v_pk_fma_f32 v[28:29], v[202:203], s[6:7], v[2:3] op_sel_hi:[1,0,1]
	v_pk_mul_f32 v[0:1], v[30:31], v[30:31]
	v_pk_add_f32 v[196:197], v[196:197], v[198:199]
	v_mov_b32_e32 v198, v168
	v_mov_b32_e32 v199, v200
	v_mov_b32_e32 v200, v169
	v_pk_add_f32 v[6:7], v[10:11], v[6:7]
	v_pk_mul_f32 v[2:3], v[28:29], v[28:29]
	v_pk_add_f32 v[198:199], v[198:199], v[200:201]
	v_pk_add_f32 v[4:5], v[4:5], v[6:7]
	v_mov_b32_e32 v6, v30
	v_mov_b32_e32 v7, v0
	v_mov_b32_e32 v0, v31
	v_pk_add_f32 v[196:197], v[196:197], v[198:199]
	v_pk_add_f32 v[0:1], v[6:7], v[0:1]
	v_mov_b32_e32 v6, v28
	v_mov_b32_e32 v7, v2
	v_mov_b32_e32 v2, v29
	v_pk_add_f32 v[8:9], v[196:197], v[8:9]
	v_pk_add_f32 v[2:3], v[6:7], v[2:3]
	ds_bpermute_b32 v192, v181, v184
	ds_bpermute_b32 v193, v181, v185
	v_pk_add_f32 v[4:5], v[8:9], v[4:5]
	v_pk_add_f32 v[0:1], v[0:1], v[2:3]
	v_cndmask_b32_e32 v8, v183, v140, vcc
	v_pk_add_f32 v[0:1], v[4:5], v[0:1]
	ds_bpermute_b32 v2, v181, v0
	ds_bpermute_b32 v3, v181, v1
	s_waitcnt lgkmcnt(2)
	v_pk_add_f32 v[4:5], v[184:185], v[192:193]
	ds_bpermute_b32 v6, v180, v4
	ds_bpermute_b32 v7, v180, v5
	s_movk_i32 s6, 0x100
	s_waitcnt lgkmcnt(2)
	v_pk_add_f32 v[0:1], v[0:1], v[2:3]
	ds_bpermute_b32 v2, v180, v0
	ds_bpermute_b32 v3, v180, v1
	s_waitcnt lgkmcnt(2)
	v_pk_add_f32 v[4:5], v[4:5], v[6:7]
	ds_write_b64 v8, v[4:5]
	v_lshl_add_u32 v4, v191, 5, s7
	v_cndmask_b32_e32 v4, v183, v4, vcc
	s_waitcnt lgkmcnt(1)
	v_pk_add_f32 v[0:1], v[0:1], v[2:3]
	ds_write_b64 v4, v[0:1]
	v_or_b32_e32 v0, s19, v172
	v_cmp_gt_u32_e64 s[6:7], s6, v172
	v_ashrrev_i32_e32 v1, 31, v0
	s_waitcnt lgkmcnt(0)
	s_barrier
	s_and_saveexec_b64 s[24:25], s[6:7]
	s_cbranch_execz .LBB0_1050
	v_lshl_add_u32 v6, v172, 5, 0
	ds_read_b128 v[2:5], v6
	ds_read_b128 v[6:9], v6 offset:16
	s_ashr_i32 s21, s20, 31
	s_waitcnt lgkmcnt(1)
	v_add_f32_e32 v2, v2, v4
	v_add_f32_e32 v3, v3, v5
	v_lshlrev_b64 v[4:5], 5, v[0:1]
	s_waitcnt lgkmcnt(0)
	v_add_f32_e32 v2, v2, v6
	v_add_f32_e32 v3, v3, v7
	v_lshl_add_u64 v[4:5], s[22:23], 0, v[4:5]
	v_add_f32_e32 v2, v2, v8
	v_add_f32_e32 v3, v3, v9
	v_lshl_add_u64 v[4:5], s[20:21], 3, v[4:5]
	global_store_dwordx2 v[4:5], v[2:3], off sc1

;     __host__ __device__ bool next(int i, Unit& u) const {
;         const long L = (long)i * G + c; if (L >= nwg) return false;
;         int wgid = (int)L; { const int q = nwg / NXCD, r = nwg % NXCD, xcd = wgid % NXCD, off = wgid / NXCD; wgid = (xcd < r ? xcd * (q + 1) : r * (q + 1) + (xcd - r) * q) + off; }
;         const int nig = WGM * nN, gid = wgid / nig, fm = gid * WGM, gsz = (nM - fm) < WGM ? (nM - fm) : WGM;
;         u.pm = fm + ((wgid % nig) % gsz); u.pn = (wgid % nig) / gsz; return true;
.LBB0_1229:
	v_readlane_b32 s10, v252, 1
	v_readlane_b32 s11, v252, 2
	s_mov_b64 s[6:7], s[10:11]
	s_mov_b64 s[8:9], s[10:11]
	v_mov_b32_e32 v8, v172
	s_andn2_b64 vcc, exec, s[16:17]
	v_readfirstlane_b32 s23, v8
	s_cbranch_vccnz .LBB0_1278
	s_ashr_i32 s44, s2, 31
	s_lshr_b32 s0, s44, 29
	s_add_i32 s5, s2, s0
	s_and_b32 s0, s5, -8
	s_sub_i32 s16, s2, s0
	s_cmp_gt_i32 s16, -1
	s_cbranch_scc0 .LBB0_1232
	s_lshl_b32 s4, s16, 5
	s_cbranch_execz .LBB0_1233
	s_branch .LBB0_1234

; __device__ __forceinline__ unsigned xb_add(unsigned* p, unsigned v) { return __hip_atomic_fetch_add(p, v, __ATOMIC_RELAXED, __HIP_MEMORY_SCOPE_AGENT); }
;     __device__ __forceinline__ void fused(f32x4 (&acc)[2][2][4][2], const Unit& u, int wr, int wc, int fr, int fq, PG8_LAS unsigned char* lds, int wid, int lane) const {
;     ...
;         for (int ai = 0; ai < 2; ++ai)
; #pragma unroll
;             for (int m = 0; m < 4; ++m) {
;                 const int rl = ai * 128 + wr * 64 + m * 16 + fr;
;                 const size_t roff = (size_t)(u.pm * 256 + rl) * 1024 + u.pn * 256 + wc * 32 + fq * 8;
;                 float s1 = 0.f, s2 = 0.f;
; #pragma unroll
;                 for (int bj = 0; bj < 2; ++bj) {
;                     float x[8];
;                     if (RES_BF16) ld8f((const bfu*)res + roff + bj * 128, x);
;                     else ld8f32((const float*)res + roff + bj * 128, x);
; #pragma unroll
;                     for (int n = 0; n < 2; ++n) {
;                         f32x4 v = acc[ai][bj][m][n];
;                         v[0] += ALPHA * x[4 * n]; v[1] += ALPHA * x[4 * n + 1]; v[2] += ALPHA * x[4 * n + 2]; v[3] += ALPHA * x[4 * n + 3];
;                         acc[ai][bj][m][n] = v;
;                         s1 += (v[0] + v[1]) + (v[2] + v[3]); s2 += (v[0] * v[0] + v[1] * v[1]) + (v[2] * v[2] + v[3] * v[3]);
;                     }
;                 }
;                 s1 += __shfl_xor(s1, 16); s1 += __shfl_xor(s1, 32); s2 += __shfl_xor(s2, 16); s2 += __shfl_xor(s2, 32);
; __device__ __forceinline__ void sample_rows_publish(unsigned* cnt_s, int bid) {
;     ...
;     if (threadIdx.x == 0) { __builtin_amdgcn_fence(__ATOMIC_RELEASE, "agent"); asm volatile("s_waitcnt vmcnt(0)" ::: "memory"); xb_add(cnt_s + (bid >> 4) * 64, 1u); }
.LBB0_1255:
	s_add_u32 s10, s66, 0x38b80000
	s_addc_u32 s11, s67, 0
	s_lshl_b32 s23, s43, 8
	v_add_u32_e32 v130, s23, v152
	s_lshl_b32 s8, s22, 8
	v_ashrrev_i32_e32 v131, 31, v130
	s_ashr_i32 s9, s8, 31
	v_lshlrev_b64 v[132:133], 11, v[130:131]
	v_lshl_add_u64 v[132:133], s[14:15], 0, v[132:133]
	s_lshl_b64 s[24:25], s[8:9], 1
	s_mov_b32 s21, 0
	v_lshl_add_u64 v[132:133], v[132:133], 0, s[24:25]
	s_lshl_b32 s20, s42, 6
	v_lshl_add_u64 v[132:133], v[132:133], 0, s[20:21]
	v_mov_b32_e32 v129, 0
	v_lshl_add_u64 v[132:133], v[132:133], 0, v[128:129]
	s_barrier
	global_load_dwordx4 v[134:137], v[132:133], off
	global_load_dwordx4 v[138:141], v[132:133], off offset:256
	s_mov_b64 s[98:99], 0x8000
	v_lshl_add_u64 v[250:251], v[132:133], 0, s[98:99]
	global_load_dwordx4 v[196:199], v[250:251], off
	global_load_dwordx4 v[200:203], v[250:251], off offset:256
	s_mov_b64 s[98:99], 0x10000
	v_lshl_add_u64 v[250:251], v[132:133], 0, s[98:99]
	global_load_dwordx4 v[204:207], v[250:251], off
	global_load_dwordx4 v[208:211], v[250:251], off offset:256
	s_mov_b64 s[98:99], 0x18000
	v_lshl_add_u64 v[250:251], v[132:133], 0, s[98:99]
	global_load_dwordx4 v[212:215], v[250:251], off
	global_load_dwordx4 v[216:219], v[250:251], off offset:256
	s_mov_b64 s[98:99], 0x40000
	v_lshl_add_u64 v[250:251], v[132:133], 0, s[98:99]
	global_load_dwordx4 v[220:223], v[250:251], off
	global_load_dwordx4 v[224:227], v[250:251], off offset:256
	s_mov_b64 s[98:99], 0x48000
	v_lshl_add_u64 v[250:251], v[132:133], 0, s[98:99]
	global_load_dwordx4 v[228:231], v[250:251], off
	global_load_dwordx4 v[232:235], v[250:251], off offset:256
	s_mov_b64 s[98:99], 0x50000
	v_lshl_add_u64 v[250:251], v[132:133], 0, s[98:99]
	global_load_dwordx4 v[236:239], v[250:251], off
	global_load_dwordx4 v[240:243], v[250:251], off offset:256
	v_readlane_b32 s98, v252, 6
	v_readlane_b32 s99, v252, 7
	s_nop 3
	s_and_saveexec_b64 s[100:101], s[98:99]
	s_cbranch_execz .Lpub_skip_p10
	s_lshl_b32 s98, s2, 2
	s_andn2_b32 s98, s98, 63
	s_lshl_b32 s98, s98, 2
	s_add_u32 s98, s3, s98
	s_addc_u32 s99, s33, 0
	v_mov_b32_e32 v250, 0
	v_mov_b32_e32 v251, 1
	global_atomic_add v250, v251, s[98:99]
.Lpub_skip_p10:
	s_mov_b64 exec, s[100:101]
	v_mbcnt_lo_u32_b32 v132, -1, 0
	v_mbcnt_hi_u32_b32 v142, -1, v132
	v_and_b32_e32 v133, 64, v142
	v_or_b32_e32 v153, 16, v152
	v_xor_b32_e32 v143, 16, v142
	v_add_u32_e32 v145, 64, v133
	v_xor_b32_e32 v144, 32, v142
	v_add_u32_e32 v132, s23, v153
	v_cmp_lt_i32_e32 vcc, v143, v145
	v_ashrrev_i32_e32 v133, 31, v132
	s_mov_b32 s6, 0x3f9837f0
	v_cndmask_b32_e32 v146, v142, v143, vcc
	v_cmp_lt_i32_e32 vcc, v144, v145
	v_lshlrev_b32_e32 v151, 2, v146
	s_waitcnt vmcnt(0)
	v_lshlrev_b32_e32 v154, 16, v135
	v_cndmask_b32_e32 v144, v142, v144, vcc
	v_lshlrev_b64 v[142:143], 11, v[132:133]
	v_lshl_add_u64 v[142:143], s[14:15], 0, v[142:143]
	v_lshl_add_u64 v[142:143], v[142:143], 0, s[24:25]
	v_lshl_add_u64 v[142:143], v[142:143], 0, s[20:21]
	v_lshl_add_u64 v[146:147], v[142:143], 0, v[128:129]
	v_lshlrev_b32_e32 v149, 2, v144
	s_waitcnt vmcnt(0)
	v_mov_b64_e32 v[142:143], v[196:197]
	v_mov_b64_e32 v[144:145], v[198:199]
	v_mov_b64_e32 v[158:159], v[200:201]
	v_mov_b64_e32 v[160:161], v[202:203]
	v_lshlrev_b32_e32 v146, 16, v134
	v_and_b32_e32 v147, 0xffff0000, v134
	v_and_b32_e32 v155, 0xffff0000, v135
	v_lshlrev_b32_e32 v156, 16, v136
	v_and_b32_e32 v157, 0xffff0000, v136
	v_lshlrev_b32_e32 v136, 16, v137
	v_and_b32_e32 v137, 0xffff0000, v137
	v_lshlrev_b32_e32 v162, 16, v138
	v_and_b32_e32 v163, 0xffff0000, v138
	v_lshlrev_b32_e32 v138, 16, v139
	v_and_b32_e32 v139, 0xffff0000, v139
	v_lshlrev_b32_e32 v164, 16, v140
	v_and_b32_e32 v165, 0xffff0000, v140
	v_lshlrev_b32_e32 v140, 16, v141
	v_and_b32_e32 v141, 0xffff0000, v141
	v_pk_fma_f32 v[134:135], v[146:147], s[6:7], v[124:125] op_sel_hi:[1,0,1]
	v_pk_fma_f32 v[126:127], v[154:155], s[6:7], v[126:127] op_sel_hi:[1,0,1]
	v_pk_fma_f32 v[124:125], v[156:157], s[6:7], v[120:121] op_sel_hi:[1,0,1]
	v_pk_fma_f32 v[122:123], v[136:137], s[6:7], v[122:123] op_sel_hi:[1,0,1]
	v_pk_fma_f32 v[120:121], v[162:163], s[6:7], v[116:117] op_sel_hi:[1,0,1]
	v_pk_fma_f32 v[118:119], v[138:139], s[6:7], v[118:119] op_sel_hi:[1,0,1]
	v_pk_fma_f32 v[116:117], v[164:165], s[6:7], v[112:113] op_sel_hi:[1,0,1]
	v_pk_fma_f32 v[112:113], v[140:141], s[6:7], v[114:115] op_sel_hi:[1,0,1]
	v_pk_add_f32 v[114:115], v[134:135], v[134:135] op_sel:[0,1] op_sel_hi:[1,0]
	v_pk_add_f32 v[136:137], v[126:127], v[126:127] op_sel:[0,1] op_sel_hi:[1,0]
	v_pk_mul_f32 v[138:139], v[134:135], v[134:135]
	v_pk_mul_f32 v[140:141], v[126:127], v[126:127]
	v_pk_mul_f32 v[146:147], v[124:125], v[124:125]
	v_mul_f32_e32 v148, v122, v122
	v_mov_b32_e32 v166, v124
	v_mov_b32_e32 v168, v122
	v_pk_fma_f32 v[174:175], v[122:123], v[122:123], v[148:149] op_sel_hi:[1,1,0]
	v_mov_b32_e32 v167, v138
	v_mov_b32_e32 v138, v125
	v_mov_b32_e32 v169, v140
	v_mov_b32_e32 v140, v123
	v_mov_b32_e32 v115, v146
	v_mov_b32_e32 v137, v147
	v_pk_add_f32 v[138:139], v[166:167], v[138:139]
	v_pk_add_f32 v[140:141], v[168:169], v[140:141]
	v_pk_add_f32 v[114:115], v[114:115], v[136:137]
	v_mov_b32_e32 v174, v129
	v_pk_mul_f32 v[154:155], v[120:121], v[120:121]
	v_pk_mul_f32 v[156:157], v[118:119], v[118:119]
	v_pk_add_f32 v[138:139], v[138:139], v[140:141]
	v_pk_add_f32 v[114:115], v[114:115], v[174:175]
	v_mov_b32_e32 v170, v120
	v_mov_b32_e32 v171, v154
	v_mov_b32_e32 v154, v121
	v_pk_add_f32 v[114:115], v[138:139], v[114:115]
	v_mov_b32_e32 v138, v118
	v_mov_b32_e32 v139, v156
	v_mov_b32_e32 v156, v119
	v_pk_add_f32 v[136:137], v[170:171], v[154:155]
	v_pk_add_f32 v[138:139], v[138:139], v[156:157]
	v_pk_mul_f32 v[162:163], v[116:117], v[116:117]
	v_pk_mul_f32 v[164:165], v[112:113], v[112:113]
	v_pk_add_f32 v[136:137], v[136:137], v[138:139]
	v_mov_b32_e32 v138, v112
	v_pk_add_f32 v[114:115], v[114:115], v[136:137]
	v_mov_b32_e32 v136, v116
	v_mov_b32_e32 v137, v162
	v_mov_b32_e32 v162, v117
	v_mov_b32_e32 v139, v164
	v_mov_b32_e32 v164, v113
	v_pk_add_f32 v[136:137], v[136:137], v[162:163]
	v_pk_add_f32 v[138:139], v[138:139], v[164:165]
	v_or_b32_e32 v154, 32, v152
	v_pk_add_f32 v[136:137], v[136:137], v[138:139]
	s_lshl_b32 s7, s42, 3
	v_pk_add_f32 v[114:115], v[114:115], v[136:137]
	ds_bpermute_b32 v136, v151, v114
	ds_bpermute_b32 v137, v151, v115
	s_add_i32 s7, s7, 0
	v_lshl_add_u32 v148, v172, 3, 0
	v_add_u32_e32 v156, 0x3000, v148
	v_lshl_add_u32 v155, v152, 5, s7
	s_waitcnt lgkmcnt(0)
; #define PG8_LAS __attribute__((address_space(3)))
;     __device__ __forceinline__ void fused(f32x4 (&acc)[2][2][4][2], const Unit& u, int wr, int wc, int fr, int fq, PG8_LAS unsigned char* lds, int wid, int lane) const {
;     ...
;         for (int ai = 0; ai < 2; ++ai)
; #pragma unroll
;             for (int m = 0; m < 4; ++m) {
;                 const int rl = ai * 128 + wr * 64 + m * 16 + fr;
;                 const size_t roff = (size_t)(u.pm * 256 + rl) * 1024 + u.pn * 256 + wc * 32 + fq * 8;
;                 float s1 = 0.f, s2 = 0.f;
; #pragma unroll
;                 for (int bj = 0; bj < 2; ++bj) {
;                     float x[8];
;                     if (RES_BF16) ld8f((const bfu*)res + roff + bj * 128, x);
;                     else ld8f32((const float*)res + roff + bj * 128, x);
; #pragma unroll
;                     for (int n = 0; n < 2; ++n) {
;                         f32x4 v = acc[ai][bj][m][n];
;                         v[0] += ALPHA * x[4 * n]; v[1] += ALPHA * x[4 * n + 1]; v[2] += ALPHA * x[4 * n + 2]; v[3] += ALPHA * x[4 * n + 3];
;                         acc[ai][bj][m][n] = v;
;                         s1 += (v[0] + v[1]) + (v[2] + v[3]); s2 += (v[0] * v[0] + v[1] * v[1]) + (v[2] * v[2] + v[3] * v[3]);
;                     }
;                 }
;                 s1 += __shfl_xor(s1, 16); s1 += __shfl_xor(s1, 32); s2 += __shfl_xor(s2, 16); s2 += __shfl_xor(s2, 32);
;                 {
;                     PG8_LAS float* pd = (fq == 0) ? P + (rl * 4 + wc) * 2 : (PG8_LAS float*)(lds + 12288) + tid * 2;
;                     pd[0] = s1; pd[1] = s2;
;                 }
	v_pk_add_f32 v[138:139], v[114:115], v[136:137]
	v_add_u32_e32 v136, s23, v154
	v_ashrrev_i32_e32 v137, 31, v136
	v_lshlrev_b64 v[140:141], 11, v[136:137]
	v_lshl_add_u64 v[140:141], s[14:15], 0, v[140:141]
	v_lshl_add_u64 v[140:141], v[140:141], 0, s[24:25]
	v_lshl_add_u64 v[140:141], v[140:141], 0, s[20:21]
	v_lshl_add_u64 v[140:141], v[140:141], 0, v[128:129]
	v_mov_b64_e32 v[162:163], v[204:205]
	v_mov_b64_e32 v[164:165], v[206:207]
	s_waitcnt vmcnt(2)
	v_lshlrev_b32_e32 v166, 16, v144
	v_and_b32_e32 v167, 0xffff0000, v144
	v_lshlrev_b32_e32 v144, 16, v145
	v_and_b32_e32 v145, 0xffff0000, v145
	v_lshlrev_b32_e32 v114, 16, v142
	v_and_b32_e32 v115, 0xffff0000, v142
	v_lshlrev_b32_e32 v142, 16, v143
	v_and_b32_e32 v143, 0xffff0000, v143
	v_pk_fma_f32 v[106:107], v[144:145], s[6:7], v[106:107] op_sel_hi:[1,0,1]
	v_pk_fma_f32 v[114:115], v[114:115], s[6:7], v[108:109] op_sel_hi:[1,0,1]
	v_pk_fma_f32 v[110:111], v[142:143], s[6:7], v[110:111] op_sel_hi:[1,0,1]
	v_pk_fma_f32 v[108:109], v[166:167], s[6:7], v[104:105] op_sel_hi:[1,0,1]
	v_mul_f32_e32 v104, v106, v106
	v_pk_add_f32 v[168:169], v[114:115], v[114:115] op_sel:[0,1] op_sel_hi:[1,0]
	v_pk_add_f32 v[170:171], v[110:111], v[110:111] op_sel:[0,1] op_sel_hi:[1,0]
	v_pk_mul_f32 v[144:145], v[108:109], v[108:109]
	v_pk_fma_f32 v[166:167], v[106:107], v[106:107], v[104:105] op_sel_hi:[1,1,0]
	s_waitcnt vmcnt(1)
	v_lshlrev_b32_e32 v104, 16, v158
	v_and_b32_e32 v105, 0xffff0000, v158
	v_pk_mul_f32 v[174:175], v[114:115], v[114:115]
	v_lshlrev_b32_e32 v158, 16, v159
	v_and_b32_e32 v159, 0xffff0000, v159
	v_lshlrev_b32_e32 v178, 16, v160
	v_and_b32_e32 v179, 0xffff0000, v160
	v_pk_fma_f32 v[100:101], v[104:105], s[6:7], v[100:101] op_sel_hi:[1,0,1]
	v_mov_b32_e32 v169, v144
	v_mov_b32_e32 v171, v145
	v_pk_mul_f32 v[176:177], v[110:111], v[110:111]
	v_pk_fma_f32 v[104:105], v[158:159], s[6:7], v[102:103] op_sel_hi:[1,0,1]
	v_pk_mul_f32 v[158:159], v[100:101], v[100:101]
	v_pk_fma_f32 v[102:103], v[178:179], s[6:7], v[96:97] op_sel_hi:[1,0,1]
	v_mov_b32_e32 v178, v108
	v_mov_b32_e32 v179, v174
	v_mov_b32_e32 v174, v109
	v_pk_add_f32 v[144:145], v[168:169], v[170:171]
	v_mov_b32_e32 v166, v129
	v_pk_mul_f32 v[180:181], v[104:105], v[104:105]
	v_pk_add_f32 v[174:175], v[178:179], v[174:175]
	v_mov_b32_e32 v178, v106
	v_mov_b32_e32 v179, v176
	v_mov_b32_e32 v176, v107
	v_pk_add_f32 v[144:145], v[144:145], v[166:167]
	v_mov_b32_e32 v166, v100
	v_mov_b32_e32 v167, v158
	v_mov_b32_e32 v158, v101
	v_pk_add_f32 v[176:177], v[178:179], v[176:177]
	v_pk_add_f32 v[158:159], v[166:167], v[158:159]
	v_mov_b32_e32 v166, v104
	v_mov_b32_e32 v167, v180
	v_mov_b32_e32 v180, v105
	v_lshlrev_b32_e32 v160, 16, v161
	v_and_b32_e32 v161, 0xffff0000, v161
	v_pk_add_f32 v[174:175], v[174:175], v[176:177]
	v_pk_add_f32 v[166:167], v[166:167], v[180:181]
	v_pk_fma_f32 v[96:97], v[160:161], s[6:7], v[98:99] op_sel_hi:[1,0,1]
	v_pk_mul_f32 v[98:99], v[102:103], v[102:103]
	v_pk_add_f32 v[144:145], v[174:175], v[144:145]
	v_pk_add_f32 v[158:159], v[158:159], v[166:167]
	v_pk_mul_f32 v[160:161], v[96:97], v[96:97]
	v_pk_add_f32 v[144:145], v[144:145], v[158:159]
	v_mov_b32_e32 v158, v102
	v_mov_b32_e32 v159, v98
	v_mov_b32_e32 v98, v103
	v_pk_add_f32 v[98:99], v[158:159], v[98:99]
	v_mov_b32_e32 v158, v96
	v_mov_b32_e32 v159, v160
	v_mov_b32_e32 v160, v97
	v_pk_add_f32 v[158:159], v[158:159], v[160:161]
	ds_bpermute_b32 v146, v149, v138
	ds_bpermute_b32 v147, v149, v139
	v_pk_add_f32 v[98:99], v[98:99], v[158:159]
	v_cmp_eq_u32_e32 vcc, 0, v150
	v_pk_add_f32 v[98:99], v[144:145], v[98:99]
	ds_bpermute_b32 v144, v151, v98
	ds_bpermute_b32 v145, v151, v99
	v_cndmask_b32_e32 v157, v156, v155, vcc
	v_or_b32_e32 v155, 48, v152
	s_waitcnt lgkmcnt(2)
	v_pk_add_f32 v[166:167], v[138:139], v[146:147]
	v_add_u32_e32 v138, s23, v155
	v_ashrrev_i32_e32 v139, 31, v138
	s_waitcnt lgkmcnt(0)
	v_pk_add_f32 v[168:169], v[98:99], v[144:145]
	v_lshlrev_b64 v[144:145], 11, v[138:139]
	v_lshl_add_u64 v[144:145], s[14:15], 0, v[144:145]
	v_lshl_add_u64 v[144:145], v[144:145], 0, s[24:25]
	v_lshl_add_u64 v[144:145], v[144:145], 0, s[20:21]
	v_lshl_add_u64 v[158:159], v[144:145], 0, v[128:129]
	v_mov_b64_e32 v[144:145], v[212:213]
	v_mov_b64_e32 v[146:147], v[214:215]
	s_waitcnt vmcnt(1)
	v_lshlrev_b32_e32 v160, 16, v163
	v_mov_b64_e32 v[140:141], v[208:209]
	v_mov_b64_e32 v[142:143], v[210:211]
	v_and_b32_e32 v161, 0xffff0000, v163
	v_pk_fma_f32 v[94:95], v[160:161], s[6:7], v[94:95] op_sel_hi:[1,0,1]
	v_mov_b64_e32 v[158:159], v[216:217]
	v_mov_b64_e32 v[160:161], v[218:219]
	v_lshlrev_b32_e32 v98, 16, v162
	v_and_b32_e32 v99, 0xffff0000, v162
	v_lshlrev_b32_e32 v162, 16, v164
	v_and_b32_e32 v163, 0xffff0000, v164
	v_lshlrev_b32_e32 v164, 16, v165
	v_and_b32_e32 v165, 0xffff0000, v165
	v_pk_fma_f32 v[90:91], v[164:165], s[6:7], v[90:91] op_sel_hi:[1,0,1]
	v_pk_fma_f32 v[98:99], v[98:99], s[6:7], v[92:93] op_sel_hi:[1,0,1]
	v_pk_fma_f32 v[92:93], v[162:163], s[6:7], v[88:89] op_sel_hi:[1,0,1]
	v_mul_f32_e32 v88, v90, v90
	v_pk_add_f32 v[174:175], v[98:99], v[98:99] op_sel:[0,1] op_sel_hi:[1,0]
	v_pk_add_f32 v[176:177], v[94:95], v[94:95] op_sel:[0,1] op_sel_hi:[1,0]
	v_pk_mul_f32 v[162:163], v[92:93], v[92:93]
	v_pk_fma_f32 v[164:165], v[90:91], v[90:91], v[88:89] op_sel_hi:[1,1,0]
	v_pk_mul_f32 v[178:179], v[98:99], v[98:99]
	v_mov_b32_e32 v175, v162
	v_mov_b32_e32 v177, v163
	v_pk_mul_f32 v[180:181], v[94:95], v[94:95]
	v_pk_add_f32 v[162:163], v[174:175], v[176:177]
	v_mov_b32_e32 v164, v129
	v_pk_add_f32 v[162:163], v[162:163], v[164:165]
	ds_write_b64 v157, v[166:167]
	v_add_u32_e32 v157, 0x80, v152
	ds_bpermute_b32 v170, v149, v168
	ds_bpermute_b32 v171, v149, v169
	s_waitcnt vmcnt(2)
; #define PG8_LAS __attribute__((address_space(3)))
;     __device__ __forceinline__ void fused(f32x4 (&acc)[2][2][4][2], const Unit& u, int wr, int wc, int fr, int fq, PG8_LAS unsigned char* lds, int wid, int lane) const {
;     ...
;         for (int ai = 0; ai < 2; ++ai)
; #pragma unroll
;             for (int m = 0; m < 4; ++m) {
;                 const int rl = ai * 128 + wr * 64 + m * 16 + fr;
;                 const size_t roff = (size_t)(u.pm * 256 + rl) * 1024 + u.pn * 256 + wc * 32 + fq * 8;
;                 float s1 = 0.f, s2 = 0.f;
; #pragma unroll
;                 for (int bj = 0; bj < 2; ++bj) {
;                     float x[8];
;                     if (RES_BF16) ld8f((const bfu*)res + roff + bj * 128, x);
;                     else ld8f32((const float*)res + roff + bj * 128, x);
; #pragma unroll
;                     for (int n = 0; n < 2; ++n) {
;                         f32x4 v = acc[ai][bj][m][n];
;                         v[0] += ALPHA * x[4 * n]; v[1] += ALPHA * x[4 * n + 1]; v[2] += ALPHA * x[4 * n + 2]; v[3] += ALPHA * x[4 * n + 3];
;                         acc[ai][bj][m][n] = v;
;                         s1 += (v[0] + v[1]) + (v[2] + v[3]); s2 += (v[0] * v[0] + v[1] * v[1]) + (v[2] * v[2] + v[3] * v[3]);
;                     }
;                 }
;                 s1 += __shfl_xor(s1, 16); s1 += __shfl_xor(s1, 32); s2 += __shfl_xor(s2, 16); s2 += __shfl_xor(s2, 32);
;                 {
;                     PG8_LAS float* pd = (fq == 0) ? P + (rl * 4 + wc) * 2 : (PG8_LAS float*)(lds + 12288) + tid * 2;
;                     pd[0] = s1; pd[1] = s2;
;                 }
	v_lshlrev_b32_e32 v174, 16, v146
	v_and_b32_e32 v175, 0xffff0000, v146
	s_waitcnt vmcnt(1)
	v_lshlrev_b32_e32 v88, 16, v140
	v_and_b32_e32 v89, 0xffff0000, v140
	v_lshlrev_b32_e32 v140, 16, v141
	v_and_b32_e32 v141, 0xffff0000, v141
	v_lshlrev_b32_e32 v182, 16, v142
	v_and_b32_e32 v183, 0xffff0000, v142
	v_pk_fma_f32 v[84:85], v[88:89], s[6:7], v[84:85] op_sel_hi:[1,0,1]
	v_pk_fma_f32 v[88:89], v[140:141], s[6:7], v[86:87] op_sel_hi:[1,0,1]
	v_pk_mul_f32 v[140:141], v[84:85], v[84:85]
	v_pk_fma_f32 v[86:87], v[182:183], s[6:7], v[80:81] op_sel_hi:[1,0,1]
	v_mov_b32_e32 v182, v92
	v_mov_b32_e32 v183, v178
	v_mov_b32_e32 v178, v93
	v_pk_mul_f32 v[184:185], v[88:89], v[88:89]
	v_pk_add_f32 v[178:179], v[182:183], v[178:179]
	v_mov_b32_e32 v182, v90
	v_mov_b32_e32 v183, v180
	v_mov_b32_e32 v180, v91
	v_mov_b32_e32 v164, v84
	v_mov_b32_e32 v165, v140
	v_mov_b32_e32 v140, v85
	v_pk_add_f32 v[180:181], v[182:183], v[180:181]
	v_pk_add_f32 v[140:141], v[164:165], v[140:141]
	v_mov_b32_e32 v164, v88
	v_mov_b32_e32 v165, v184
	v_mov_b32_e32 v184, v89
	v_lshlrev_b32_e32 v142, 16, v143
	v_and_b32_e32 v143, 0xffff0000, v143
	v_pk_add_f32 v[178:179], v[178:179], v[180:181]
	v_pk_add_f32 v[164:165], v[164:165], v[184:185]
	v_pk_fma_f32 v[80:81], v[142:143], s[6:7], v[82:83] op_sel_hi:[1,0,1]
	v_pk_mul_f32 v[82:83], v[86:87], v[86:87]
	v_pk_add_f32 v[162:163], v[178:179], v[162:163]
	v_pk_add_f32 v[140:141], v[140:141], v[164:165]
	v_pk_mul_f32 v[142:143], v[80:81], v[80:81]
	v_pk_add_f32 v[140:141], v[162:163], v[140:141]
	v_mov_b32_e32 v162, v86
	v_mov_b32_e32 v163, v82
	v_mov_b32_e32 v82, v87
	v_pk_add_f32 v[82:83], v[162:163], v[82:83]
	v_mov_b32_e32 v162, v80
	v_mov_b32_e32 v163, v142
	v_mov_b32_e32 v142, v81
	v_pk_add_f32 v[142:143], v[162:163], v[142:143]
	v_lshlrev_b32_e32 v146, 16, v147
	v_pk_add_f32 v[82:83], v[82:83], v[142:143]
	v_and_b32_e32 v147, 0xffff0000, v147
	v_pk_add_f32 v[82:83], v[140:141], v[82:83]
	ds_bpermute_b32 v140, v151, v82
	ds_bpermute_b32 v141, v151, v83
	v_pk_fma_f32 v[74:75], v[146:147], s[6:7], v[74:75] op_sel_hi:[1,0,1]
	v_lshl_add_u32 v142, v153, 5, s7
	v_cndmask_b32_e32 v173, v156, v142, vcc
	s_waitcnt lgkmcnt(2)
	v_pk_add_f32 v[142:143], v[168:169], v[170:171]
	s_waitcnt lgkmcnt(0)
	v_pk_add_f32 v[166:167], v[82:83], v[140:141]
	v_add_u32_e32 v140, s23, v157
	v_ashrrev_i32_e32 v141, 31, v140
	v_lshlrev_b32_e32 v82, 16, v144
	v_lshlrev_b64 v[162:163], 11, v[140:141]
	v_and_b32_e32 v83, 0xffff0000, v144
	v_lshl_add_u64 v[162:163], s[14:15], 0, v[162:163]
	v_lshlrev_b32_e32 v144, 16, v145
	v_and_b32_e32 v145, 0xffff0000, v145
	v_pk_fma_f32 v[82:83], v[82:83], s[6:7], v[76:77] op_sel_hi:[1,0,1]
	v_pk_fma_f32 v[76:77], v[174:175], s[6:7], v[72:73] op_sel_hi:[1,0,1]
	v_mul_f32_e32 v72, v74, v74
	v_lshl_add_u64 v[162:163], v[162:163], 0, s[24:25]
	v_pk_fma_f32 v[78:79], v[144:145], s[6:7], v[78:79] op_sel_hi:[1,0,1]
	v_pk_fma_f32 v[184:185], v[74:75], v[74:75], v[72:73] op_sel_hi:[1,1,0]
	s_waitcnt vmcnt(0)
	v_lshlrev_b32_e32 v72, 16, v158
	v_and_b32_e32 v73, 0xffff0000, v158
	v_lshl_add_u64 v[162:163], v[162:163], 0, s[20:21]
	v_pk_add_f32 v[176:177], v[82:83], v[82:83] op_sel:[0,1] op_sel_hi:[1,0]
	v_pk_add_f32 v[178:179], v[78:79], v[78:79] op_sel:[0,1] op_sel_hi:[1,0]
	v_pk_mul_f32 v[174:175], v[76:77], v[76:77]
	v_lshlrev_b32_e32 v158, 16, v159
	v_and_b32_e32 v159, 0xffff0000, v159
	v_pk_fma_f32 v[68:69], v[72:73], s[6:7], v[68:69] op_sel_hi:[1,0,1]
	v_lshl_add_u64 v[170:171], v[162:163], 0, v[128:129]
	v_pk_fma_f32 v[72:73], v[158:159], s[6:7], v[70:71] op_sel_hi:[1,0,1]
	v_pk_mul_f32 v[158:159], v[68:69], v[68:69]
	v_mov_b32_e32 v177, v174
	v_mov_b32_e32 v179, v175
	v_mov_b64_e32 v[162:163], v[220:221]
	v_mov_b64_e32 v[164:165], v[222:223]
	v_mov_b64_e32 v[144:145], v[224:225]
	v_mov_b64_e32 v[146:147], v[226:227]
	v_pk_mul_f32 v[180:181], v[82:83], v[82:83]
	v_lshlrev_b32_e32 v186, 16, v160
	v_and_b32_e32 v187, 0xffff0000, v160
	v_pk_mul_f32 v[170:171], v[72:73], v[72:73]
	v_pk_add_f32 v[174:175], v[176:177], v[178:179]
	v_mov_b32_e32 v176, v68
	v_mov_b32_e32 v177, v158
	v_mov_b32_e32 v158, v69
	v_pk_mul_f32 v[182:183], v[78:79], v[78:79]
	v_lshlrev_b32_e32 v160, 16, v161
	v_and_b32_e32 v161, 0xffff0000, v161
	v_pk_fma_f32 v[70:71], v[186:187], s[6:7], v[64:65] op_sel_hi:[1,0,1]
	v_mov_b32_e32 v186, v76
	v_mov_b32_e32 v187, v180
	v_mov_b32_e32 v180, v77
	v_pk_add_f32 v[158:159], v[176:177], v[158:159]
	v_mov_b32_e32 v176, v72
	v_mov_b32_e32 v177, v170
	v_mov_b32_e32 v170, v73
	v_pk_fma_f32 v[64:65], v[160:161], s[6:7], v[66:67] op_sel_hi:[1,0,1]
	v_pk_mul_f32 v[66:67], v[70:71], v[70:71]
	v_pk_add_f32 v[180:181], v[186:187], v[180:181]
	v_mov_b32_e32 v186, v74
	v_mov_b32_e32 v187, v182
	v_mov_b32_e32 v182, v75
	v_pk_add_f32 v[170:171], v[176:177], v[170:171]
	v_pk_mul_f32 v[160:161], v[64:65], v[64:65]
	v_pk_add_f32 v[182:183], v[186:187], v[182:183]
	v_mov_b32_e32 v184, v129
	v_pk_add_f32 v[158:159], v[158:159], v[170:171]
	v_mov_b32_e32 v170, v70
	v_mov_b32_e32 v171, v66
	v_mov_b32_e32 v66, v71
	v_pk_add_f32 v[180:181], v[180:181], v[182:183]
	v_pk_add_f32 v[174:175], v[174:175], v[184:185]
	v_pk_add_f32 v[66:67], v[170:171], v[66:67]
	v_mov_b32_e32 v170, v64
	v_mov_b32_e32 v171, v160
	v_mov_b32_e32 v160, v65
	v_pk_add_f32 v[174:175], v[180:181], v[174:175]
	v_pk_add_f32 v[160:161], v[170:171], v[160:161]
	v_pk_add_f32 v[158:159], v[174:175], v[158:159]
	v_pk_add_f32 v[66:67], v[66:67], v[160:161]
	ds_write_b64 v173, v[142:143]
	v_pk_add_f32 v[66:67], v[158:159], v[66:67]
	ds_bpermute_b32 v158, v151, v66
	ds_bpermute_b32 v159, v151, v67
	v_lshl_add_u32 v142, v154, 5, s7
	v_cndmask_b32_e32 v173, v156, v142, vcc
	ds_bpermute_b32 v168, v149, v166
	ds_bpermute_b32 v169, v149, v167
	s_waitcnt lgkmcnt(2)
; #define PG8_LAS __attribute__((address_space(3)))
;     __device__ __forceinline__ void fused(f32x4 (&acc)[2][2][4][2], const Unit& u, int wr, int wc, int fr, int fq, PG8_LAS unsigned char* lds, int wid, int lane) const {
;     ...
;         for (int ai = 0; ai < 2; ++ai)
; #pragma unroll
;             for (int m = 0; m < 4; ++m) {
;                 const int rl = ai * 128 + wr * 64 + m * 16 + fr;
;                 const size_t roff = (size_t)(u.pm * 256 + rl) * 1024 + u.pn * 256 + wc * 32 + fq * 8;
;                 float s1 = 0.f, s2 = 0.f;
; #pragma unroll
;                 for (int bj = 0; bj < 2; ++bj) {
;                     float x[8];
;                     if (RES_BF16) ld8f((const bfu*)res + roff + bj * 128, x);
;                     else ld8f32((const float*)res + roff + bj * 128, x);
; #pragma unroll
;                     for (int n = 0; n < 2; ++n) {
;                         f32x4 v = acc[ai][bj][m][n];
;                         v[0] += ALPHA * x[4 * n]; v[1] += ALPHA * x[4 * n + 1]; v[2] += ALPHA * x[4 * n + 2]; v[3] += ALPHA * x[4 * n + 3];
;                         acc[ai][bj][m][n] = v;
;                         s1 += (v[0] + v[1]) + (v[2] + v[3]); s2 += (v[0] * v[0] + v[1] * v[1]) + (v[2] * v[2] + v[3] * v[3]);
;                     }
;                 }
;                 s1 += __shfl_xor(s1, 16); s1 += __shfl_xor(s1, 32); s2 += __shfl_xor(s2, 16); s2 += __shfl_xor(s2, 32);
;                 {
;                     PG8_LAS float* pd = (fq == 0) ? P + (rl * 4 + wc) * 2 : (PG8_LAS float*)(lds + 12288) + tid * 2;
;                     pd[0] = s1; pd[1] = s2;
;                 }
	v_pk_add_f32 v[174:175], v[66:67], v[158:159]
	v_add_u32_e32 v158, 0x90, v152
	v_add_u32_e32 v142, s23, v158
	v_ashrrev_i32_e32 v143, 31, v142
	v_lshlrev_b64 v[160:161], 11, v[142:143]
	v_lshl_add_u64 v[160:161], s[14:15], 0, v[160:161]
	v_lshl_add_u64 v[160:161], v[160:161], 0, s[24:25]
	v_lshl_add_u64 v[160:161], v[160:161], 0, s[20:21]
	v_lshl_add_u64 v[160:161], v[160:161], 0, v[128:129]
	s_waitcnt lgkmcnt(0)
	v_pk_add_f32 v[170:171], v[166:167], v[168:169]
	v_mov_b64_e32 v[166:167], v[228:229]
	v_mov_b64_e32 v[168:169], v[230:231]
	ds_bpermute_b32 v176, v149, v174
	ds_bpermute_b32 v177, v149, v175
	ds_write_b64 v173, v[170:171]
	v_add_u32_e32 v159, 0xa0, v152
	s_waitcnt vmcnt(2)
	v_lshlrev_b32_e32 v178, 16, v164
	v_and_b32_e32 v179, 0xffff0000, v164
	v_lshlrev_b32_e32 v164, 16, v165
	v_and_b32_e32 v165, 0xffff0000, v165
	v_lshlrev_b32_e32 v66, 16, v162
	v_and_b32_e32 v67, 0xffff0000, v162
	v_lshlrev_b32_e32 v162, 16, v163
	v_and_b32_e32 v163, 0xffff0000, v163
	v_pk_fma_f32 v[58:59], v[164:165], s[6:7], v[58:59] op_sel_hi:[1,0,1]
	v_pk_fma_f32 v[66:67], v[66:67], s[6:7], v[60:61] op_sel_hi:[1,0,1]
	v_pk_fma_f32 v[62:63], v[162:163], s[6:7], v[62:63] op_sel_hi:[1,0,1]
	v_pk_fma_f32 v[60:61], v[178:179], s[6:7], v[56:57] op_sel_hi:[1,0,1]
	v_mul_f32_e32 v56, v58, v58
	v_mov_b64_e32 v[160:161], v[232:233]
	v_mov_b64_e32 v[162:163], v[234:235]
	v_pk_add_f32 v[180:181], v[66:67], v[66:67] op_sel:[0,1] op_sel_hi:[1,0]
	v_pk_add_f32 v[182:183], v[62:63], v[62:63] op_sel:[0,1] op_sel_hi:[1,0]
	v_pk_mul_f32 v[164:165], v[60:61], v[60:61]
	v_pk_fma_f32 v[178:179], v[58:59], v[58:59], v[56:57] op_sel_hi:[1,1,0]
	s_waitcnt vmcnt(2)
	v_lshlrev_b32_e32 v56, 16, v144
	v_and_b32_e32 v57, 0xffff0000, v144
	v_pk_mul_f32 v[184:185], v[66:67], v[66:67]
	v_lshlrev_b32_e32 v144, 16, v145
	v_and_b32_e32 v145, 0xffff0000, v145
	v_lshlrev_b32_e32 v188, 16, v146
	v_and_b32_e32 v189, 0xffff0000, v146
	v_pk_fma_f32 v[52:53], v[56:57], s[6:7], v[52:53] op_sel_hi:[1,0,1]
	v_mov_b32_e32 v181, v164
	v_mov_b32_e32 v183, v165
	v_pk_mul_f32 v[186:187], v[62:63], v[62:63]
	v_pk_fma_f32 v[56:57], v[144:145], s[6:7], v[54:55] op_sel_hi:[1,0,1]
	v_pk_mul_f32 v[144:145], v[52:53], v[52:53]
	v_pk_fma_f32 v[54:55], v[188:189], s[6:7], v[48:49] op_sel_hi:[1,0,1]
	v_mov_b32_e32 v188, v60
	v_mov_b32_e32 v189, v184
	v_mov_b32_e32 v184, v61
	v_pk_add_f32 v[164:165], v[180:181], v[182:183]
	v_mov_b32_e32 v178, v129
	v_pk_mul_f32 v[190:191], v[56:57], v[56:57]
	v_pk_add_f32 v[184:185], v[188:189], v[184:185]
	v_mov_b32_e32 v188, v58
	v_mov_b32_e32 v189, v186
	v_mov_b32_e32 v186, v59
	v_pk_add_f32 v[164:165], v[164:165], v[178:179]
	v_mov_b32_e32 v178, v52
	v_mov_b32_e32 v179, v144
	v_mov_b32_e32 v144, v53
	v_pk_add_f32 v[186:187], v[188:189], v[186:187]
	v_pk_add_f32 v[144:145], v[178:179], v[144:145]
	v_mov_b32_e32 v178, v56
	v_mov_b32_e32 v179, v190
	v_mov_b32_e32 v190, v57
	v_lshlrev_b32_e32 v146, 16, v147
	v_and_b32_e32 v147, 0xffff0000, v147
	v_pk_add_f32 v[184:185], v[184:185], v[186:187]
	v_pk_add_f32 v[178:179], v[178:179], v[190:191]
	v_pk_fma_f32 v[48:49], v[146:147], s[6:7], v[50:51] op_sel_hi:[1,0,1]
	v_pk_mul_f32 v[50:51], v[54:55], v[54:55]
	v_pk_add_f32 v[164:165], v[184:185], v[164:165]
	v_pk_add_f32 v[144:145], v[144:145], v[178:179]
	v_pk_mul_f32 v[146:147], v[48:49], v[48:49]
	v_pk_add_f32 v[144:145], v[164:165], v[144:145]
	v_mov_b32_e32 v164, v54
	v_mov_b32_e32 v165, v50
	v_mov_b32_e32 v50, v55
	v_pk_add_f32 v[50:51], v[164:165], v[50:51]
	v_mov_b32_e32 v164, v48
	v_mov_b32_e32 v165, v146
	v_mov_b32_e32 v146, v49
	v_pk_add_f32 v[146:147], v[164:165], v[146:147]
	s_waitcnt vmcnt(1)
	v_lshlrev_b32_e32 v164, 16, v168
	v_pk_add_f32 v[50:51], v[50:51], v[146:147]
	v_lshl_add_u32 v146, v155, 5, s7
	v_pk_add_f32 v[50:51], v[144:145], v[50:51]
	ds_bpermute_b32 v144, v151, v50
	ds_bpermute_b32 v145, v151, v51
	v_cndmask_b32_e32 v173, v156, v146, vcc
	s_waitcnt lgkmcnt(3)
	v_pk_add_f32 v[146:147], v[174:175], v[176:177]
	v_and_b32_e32 v165, 0xffff0000, v168
	v_lshlrev_b32_e32 v168, 16, v169
	s_waitcnt lgkmcnt(0)
	v_pk_add_f32 v[174:175], v[50:51], v[144:145]
	v_lshlrev_b32_e32 v144, 16, v167
	v_and_b32_e32 v145, 0xffff0000, v167
	v_pk_fma_f32 v[46:47], v[144:145], s[6:7], v[46:47] op_sel_hi:[1,0,1]
	v_add_u32_e32 v144, s23, v159
	v_lshlrev_b32_e32 v50, 16, v166
	v_and_b32_e32 v51, 0xffff0000, v166
	v_ashrrev_i32_e32 v145, 31, v144
	v_pk_fma_f32 v[50:51], v[50:51], s[6:7], v[44:45] op_sel_hi:[1,0,1]
	v_pk_fma_f32 v[44:45], v[164:165], s[6:7], v[40:41] op_sel_hi:[1,0,1]
	v_lshlrev_b64 v[40:41], 11, v[144:145]
	v_lshl_add_u64 v[40:41], s[14:15], 0, v[40:41]
	v_lshl_add_u64 v[40:41], v[40:41], 0, s[24:25]
	v_lshl_add_u64 v[40:41], v[40:41], 0, s[20:21]
	v_lshl_add_u64 v[170:171], v[40:41], 0, v[128:129]
	v_mov_b64_e32 v[164:165], v[236:237]
	v_mov_b64_e32 v[166:167], v[238:239]
	v_and_b32_e32 v169, 0xffff0000, v169
	v_pk_fma_f32 v[42:43], v[168:169], s[6:7], v[42:43] op_sel_hi:[1,0,1]
	v_pk_add_f32 v[178:179], v[50:51], v[50:51] op_sel:[0,1] op_sel_hi:[1,0]
	v_mul_f32_e32 v40, v42, v42
	v_pk_fma_f32 v[188:189], v[42:43], v[42:43], v[40:41] op_sel_hi:[1,1,0]
	s_waitcnt vmcnt(1)
; #define PG8_LAS __attribute__((address_space(3)))
;     __device__ __forceinline__ void fused(f32x4 (&acc)[2][2][4][2], const Unit& u, int wr, int wc, int fr, int fq, PG8_LAS unsigned char* lds, int wid, int lane) const {
;     ...
;         for (int ai = 0; ai < 2; ++ai)
; #pragma unroll
;             for (int m = 0; m < 4; ++m) {
;                 const int rl = ai * 128 + wr * 64 + m * 16 + fr;
;                 const size_t roff = (size_t)(u.pm * 256 + rl) * 1024 + u.pn * 256 + wc * 32 + fq * 8;
;                 float s1 = 0.f, s2 = 0.f;
; #pragma unroll
;                 for (int bj = 0; bj < 2; ++bj) {
;                     float x[8];
;                     if (RES_BF16) ld8f((const bfu*)res + roff + bj * 128, x);
;                     else ld8f32((const float*)res + roff + bj * 128, x);
; #pragma unroll
;                     for (int n = 0; n < 2; ++n) {
;                         f32x4 v = acc[ai][bj][m][n];
;                         v[0] += ALPHA * x[4 * n]; v[1] += ALPHA * x[4 * n + 1]; v[2] += ALPHA * x[4 * n + 2]; v[3] += ALPHA * x[4 * n + 3];
;                         acc[ai][bj][m][n] = v;
;                         s1 += (v[0] + v[1]) + (v[2] + v[3]); s2 += (v[0] * v[0] + v[1] * v[1]) + (v[2] * v[2] + v[3] * v[3]);
;                     }
;                 }
;                 s1 += __shfl_xor(s1, 16); s1 += __shfl_xor(s1, 32); s2 += __shfl_xor(s2, 16); s2 += __shfl_xor(s2, 32);
;                 {
;                     PG8_LAS float* pd = (fq == 0) ? P + (rl * 4 + wc) * 2 : (PG8_LAS float*)(lds + 12288) + tid * 2;
;                     pd[0] = s1; pd[1] = s2;
;                 }
	v_lshlrev_b32_e32 v40, 16, v160
	v_and_b32_e32 v41, 0xffff0000, v160
	v_pk_add_f32 v[180:181], v[46:47], v[46:47] op_sel:[0,1] op_sel_hi:[1,0]
	v_pk_mul_f32 v[182:183], v[50:51], v[50:51]
	v_pk_mul_f32 v[186:187], v[44:45], v[44:45]
	v_lshlrev_b32_e32 v160, 16, v161
	v_and_b32_e32 v161, 0xffff0000, v161
	v_pk_fma_f32 v[40:41], v[40:41], s[6:7], v[36:37] op_sel_hi:[1,0,1]
	v_pk_mul_f32 v[184:185], v[46:47], v[46:47]
	v_pk_fma_f32 v[38:39], v[160:161], s[6:7], v[38:39] op_sel_hi:[1,0,1]
	v_pk_mul_f32 v[160:161], v[40:41], v[40:41]
	v_mov_b32_e32 v192, v44
	v_mov_b32_e32 v193, v182
	v_mov_b32_e32 v182, v45
	v_mov_b32_e32 v179, v186
	v_mov_b32_e32 v181, v187
	v_pk_mul_f32 v[190:191], v[38:39], v[38:39]
	v_pk_add_f32 v[182:183], v[192:193], v[182:183]
	v_mov_b32_e32 v192, v42
	v_mov_b32_e32 v193, v184
	v_mov_b32_e32 v184, v43
	v_pk_add_f32 v[178:179], v[178:179], v[180:181]
	v_mov_b32_e32 v180, v40
	v_mov_b32_e32 v181, v160
	v_mov_b32_e32 v160, v41
	v_lshlrev_b32_e32 v168, 16, v162
	v_and_b32_e32 v169, 0xffff0000, v162
	v_pk_add_f32 v[184:185], v[192:193], v[184:185]
	v_mov_b32_e32 v188, v129
	v_pk_add_f32 v[160:161], v[180:181], v[160:161]
	v_mov_b32_e32 v180, v38
	v_mov_b32_e32 v181, v190
	v_mov_b32_e32 v190, v39
	v_lshlrev_b32_e32 v162, 16, v163
	v_and_b32_e32 v163, 0xffff0000, v163
	v_pk_fma_f32 v[36:37], v[168:169], s[6:7], v[32:33] op_sel_hi:[1,0,1]
	v_pk_add_f32 v[182:183], v[182:183], v[184:185]
	v_pk_add_f32 v[178:179], v[178:179], v[188:189]
	v_pk_add_f32 v[180:181], v[180:181], v[190:191]
	v_pk_fma_f32 v[32:33], v[162:163], s[6:7], v[34:35] op_sel_hi:[1,0,1]
	v_pk_mul_f32 v[34:35], v[36:37], v[36:37]
	v_pk_add_f32 v[178:179], v[182:183], v[178:179]
	v_pk_add_f32 v[160:161], v[160:161], v[180:181]
	v_pk_mul_f32 v[162:163], v[32:33], v[32:33]
	v_pk_add_f32 v[160:161], v[178:179], v[160:161]
	v_mov_b32_e32 v178, v36
	v_mov_b32_e32 v179, v34
	v_mov_b32_e32 v34, v37
	v_pk_add_f32 v[34:35], v[178:179], v[34:35]
	v_mov_b32_e32 v178, v32
	v_mov_b32_e32 v179, v162
	v_mov_b32_e32 v162, v33
	v_pk_add_f32 v[162:163], v[178:179], v[162:163]
	ds_bpermute_b32 v176, v149, v174
	v_pk_add_f32 v[34:35], v[34:35], v[162:163]
	ds_bpermute_b32 v177, v149, v175
	v_pk_add_f32 v[34:35], v[160:161], v[34:35]
	ds_bpermute_b32 v160, v151, v34
	ds_bpermute_b32 v161, v151, v35
	v_mov_b64_e32 v[168:169], v[240:241]
	v_mov_b64_e32 v[170:171], v[242:243]
	ds_write_b64 v173, v[146:147]
	v_lshl_add_u32 v146, v157, 5, s7
	v_cndmask_b32_e32 v173, v156, v146, vcc
	s_waitcnt lgkmcnt(1)
	v_pk_add_f32 v[34:35], v[34:35], v[160:161]
	v_add_u32_e32 v160, 0xb0, v152
	v_add_u32_e32 v146, s23, v160
	v_ashrrev_i32_e32 v147, 31, v146
	v_pk_add_f32 v[162:163], v[174:175], v[176:177]
	ds_bpermute_b32 v178, v149, v34
	ds_bpermute_b32 v179, v149, v35
	v_lshlrev_b64 v[174:175], 11, v[146:147]
	v_lshl_add_u64 v[174:175], s[14:15], 0, v[174:175]
	v_lshl_add_u64 v[174:175], v[174:175], 0, s[24:25]
	v_lshl_add_u64 v[174:175], v[174:175], 0, s[20:21]
	v_lshl_add_u64 v[180:181], v[174:175], 0, v[128:129]
	v_lshl_add_u32 v128, v158, 5, s7
	v_cndmask_b32_e32 v128, v156, v128, vcc
	s_waitcnt lgkmcnt(0)
	v_pk_add_f32 v[34:35], v[34:35], v[178:179]
	global_load_dwordx4 v[174:177], v[180:181], off
	ds_write_b64 v173, v[162:163]
	ds_write_b64 v128, v[34:35]
	s_waitcnt vmcnt(2)
	v_lshlrev_b32_e32 v34, 16, v164
	v_and_b32_e32 v35, 0xffff0000, v164
	v_lshlrev_b32_e32 v162, 16, v165
	v_and_b32_e32 v163, 0xffff0000, v165
	v_pk_fma_f32 v[34:35], v[34:35], s[6:7], v[28:29] op_sel_hi:[1,0,1]
	v_pk_fma_f32 v[28:29], v[162:163], s[6:7], v[30:31] op_sel_hi:[1,0,1]
	global_load_dwordx4 v[162:165], v[180:181], off offset:256
	v_lshlrev_b32_e32 v178, 16, v166
	v_and_b32_e32 v179, 0xffff0000, v166
	v_lshlrev_b32_e32 v166, 16, v167
	v_and_b32_e32 v167, 0xffff0000, v167
	v_pk_fma_f32 v[26:27], v[166:167], s[6:7], v[26:27] op_sel_hi:[1,0,1]
	v_pk_fma_f32 v[30:31], v[178:179], s[6:7], v[24:25] op_sel_hi:[1,0,1]
	v_mul_f32_e32 v24, v26, v26
	v_pk_add_f32 v[182:183], v[34:35], v[34:35] op_sel:[0,1] op_sel_hi:[1,0]
	v_pk_add_f32 v[184:185], v[28:29], v[28:29] op_sel:[0,1] op_sel_hi:[1,0]
	v_pk_mul_f32 v[166:167], v[30:31], v[30:31]
	v_pk_fma_f32 v[178:179], v[26:27], v[26:27], v[24:25] op_sel_hi:[1,1,0]
	v_pk_mul_f32 v[186:187], v[34:35], v[34:35]
	v_mov_b32_e32 v183, v166
	v_mov_b32_e32 v185, v167
	v_pk_mul_f32 v[180:181], v[28:29], v[28:29]
	v_pk_add_f32 v[166:167], v[182:183], v[184:185]
	v_mov_b32_e32 v178, v129
	v_pk_add_f32 v[166:167], v[166:167], v[178:179]
	v_lshl_add_u32 v161, v159, 5, s7
	s_waitcnt vmcnt(2)
; #define PG8_LAS __attribute__((address_space(3)))
;     __device__ __forceinline__ void fused(f32x4 (&acc)[2][2][4][2], const Unit& u, int wr, int wc, int fr, int fq, PG8_LAS unsigned char* lds, int wid, int lane) const {
;     ...
;                         f32x4 v = acc[ai][bj][m][n];
;                         v[0] += ALPHA * x[4 * n]; v[1] += ALPHA * x[4 * n + 1]; v[2] += ALPHA * x[4 * n + 2]; v[3] += ALPHA * x[4 * n + 3];
;                         acc[ai][bj][m][n] = v;
;                         s1 += (v[0] + v[1]) + (v[2] + v[3]); s2 += (v[0] * v[0] + v[1] * v[1]) + (v[2] * v[2] + v[3] * v[3]);
;                     }
;                 }
;                 s1 += __shfl_xor(s1, 16); s1 += __shfl_xor(s1, 32); s2 += __shfl_xor(s2, 16); s2 += __shfl_xor(s2, 32);
;                 {
;                     PG8_LAS float* pd = (fq == 0) ? P + (rl * 4 + wc) * 2 : (PG8_LAS float*)(lds + 12288) + tid * 2;
;                     pd[0] = s1; pd[1] = s2;
;                 }
;             }
;         __syncthreads();
;         if (tid < 256) {
;             const float a = P[tid * 8] + P[tid * 8 + 2] + P[tid * 8 + 4] + P[tid * 8 + 6], b = P[tid * 8 + 1] + P[tid * 8 + 3] + P[tid * 8 + 5] + P[tid * 8 + 7];
;             const unsigned long long pk = (unsigned long long)__float_as_uint(a) | ((unsigned long long)__float_as_uint(b) << 32);
;             __hip_atomic_store(xch + ((size_t)(u.pm * 256 + tid) * 4 + u.pn), pk, __ATOMIC_RELAXED, __HIP_MEMORY_SCOPE_AGENT);
;         }
	v_lshlrev_b32_e32 v24, 16, v168
	v_and_b32_e32 v25, 0xffff0000, v168
	v_lshlrev_b32_e32 v168, 16, v169
	v_and_b32_e32 v169, 0xffff0000, v169
	v_lshlrev_b32_e32 v188, 16, v170
	v_and_b32_e32 v189, 0xffff0000, v170
	v_pk_fma_f32 v[24:25], v[24:25], s[6:7], v[20:21] op_sel_hi:[1,0,1]
	v_pk_fma_f32 v[22:23], v[168:169], s[6:7], v[22:23] op_sel_hi:[1,0,1]
	v_pk_mul_f32 v[168:169], v[24:25], v[24:25]
	v_pk_fma_f32 v[20:21], v[188:189], s[6:7], v[16:17] op_sel_hi:[1,0,1]
	v_mov_b32_e32 v188, v30
	v_mov_b32_e32 v189, v186
	v_mov_b32_e32 v186, v31
	v_pk_mul_f32 v[190:191], v[22:23], v[22:23]
	v_pk_add_f32 v[186:187], v[188:189], v[186:187]
	v_mov_b32_e32 v188, v26
	v_mov_b32_e32 v189, v180
	v_mov_b32_e32 v180, v27
	v_mov_b32_e32 v178, v24
	v_mov_b32_e32 v179, v168
	v_mov_b32_e32 v168, v25
	v_pk_add_f32 v[180:181], v[188:189], v[180:181]
	v_pk_add_f32 v[168:169], v[178:179], v[168:169]
	v_mov_b32_e32 v178, v22
	v_mov_b32_e32 v179, v190
	v_mov_b32_e32 v190, v23
	v_lshlrev_b32_e32 v170, 16, v171
	v_and_b32_e32 v171, 0xffff0000, v171
	v_pk_add_f32 v[180:181], v[186:187], v[180:181]
	v_pk_add_f32 v[178:179], v[178:179], v[190:191]
	v_pk_fma_f32 v[16:17], v[170:171], s[6:7], v[18:19] op_sel_hi:[1,0,1]
	v_pk_mul_f32 v[18:19], v[20:21], v[20:21]
	v_pk_add_f32 v[166:167], v[180:181], v[166:167]
	v_pk_add_f32 v[168:169], v[168:169], v[178:179]
	v_pk_mul_f32 v[170:171], v[16:17], v[16:17]
	v_pk_add_f32 v[166:167], v[166:167], v[168:169]
	v_mov_b32_e32 v168, v20
	v_mov_b32_e32 v169, v18
	v_mov_b32_e32 v18, v21
	v_pk_add_f32 v[18:19], v[168:169], v[18:19]
	v_mov_b32_e32 v168, v16
	v_mov_b32_e32 v169, v170
	v_mov_b32_e32 v170, v17
	v_pk_add_f32 v[168:169], v[168:169], v[170:171]
	s_waitcnt vmcnt(1)
	v_lshlrev_b32_e32 v170, 16, v175
	v_pk_add_f32 v[18:19], v[18:19], v[168:169]
	v_and_b32_e32 v171, 0xffff0000, v175
	v_pk_add_f32 v[166:167], v[166:167], v[18:19]
	v_lshlrev_b32_e32 v18, 16, v174
	v_and_b32_e32 v19, 0xffff0000, v174
	v_lshlrev_b32_e32 v174, 16, v176
	v_and_b32_e32 v175, 0xffff0000, v176
	v_lshlrev_b32_e32 v176, 16, v177
	v_and_b32_e32 v177, 0xffff0000, v177
	v_pk_fma_f32 v[18:19], v[18:19], s[6:7], v[12:13] op_sel_hi:[1,0,1]
	v_pk_fma_f32 v[12:13], v[170:171], s[6:7], v[14:15] op_sel_hi:[1,0,1]
	v_pk_fma_f32 v[14:15], v[174:175], s[6:7], v[8:9] op_sel_hi:[1,0,1]
	v_pk_fma_f32 v[8:9], v[176:177], s[6:7], v[10:11] op_sel_hi:[1,0,1]
	s_waitcnt vmcnt(0)
	v_lshlrev_b32_e32 v176, 16, v162
	v_and_b32_e32 v177, 0xffff0000, v162
	v_pk_mul_f32 v[180:181], v[18:19], v[18:19]
	v_mul_f32_e32 v128, v8, v8
	v_lshlrev_b32_e32 v162, 16, v163
	v_and_b32_e32 v163, 0xffff0000, v163
	v_pk_fma_f32 v[4:5], v[176:177], s[6:7], v[4:5] op_sel_hi:[1,0,1]
	v_pk_add_f32 v[170:171], v[18:19], v[18:19] op_sel:[0,1] op_sel_hi:[1,0]
	v_pk_add_f32 v[178:179], v[12:13], v[12:13] op_sel:[0,1] op_sel_hi:[1,0]
	v_pk_mul_f32 v[182:183], v[12:13], v[12:13]
	v_pk_mul_f32 v[10:11], v[14:15], v[14:15]
	v_pk_fma_f32 v[174:175], v[8:9], v[8:9], v[128:129] op_sel_hi:[1,1,0]
	v_pk_fma_f32 v[6:7], v[162:163], s[6:7], v[6:7] op_sel_hi:[1,0,1]
	v_pk_mul_f32 v[162:163], v[4:5], v[4:5]
	v_mov_b32_e32 v186, v14
	v_mov_b32_e32 v187, v180
	v_mov_b32_e32 v180, v15
	v_pk_mul_f32 v[176:177], v[6:7], v[6:7]
	v_pk_add_f32 v[180:181], v[186:187], v[180:181]
	v_mov_b32_e32 v186, v8
	v_mov_b32_e32 v187, v182
	v_mov_b32_e32 v182, v9
	v_mov_b32_e32 v171, v10
	v_mov_b32_e32 v179, v11
	v_mov_b32_e32 v174, v129
	v_mov_b32_e32 v128, v4
	v_mov_b32_e32 v129, v162
	v_mov_b32_e32 v162, v5
	v_lshlrev_b32_e32 v184, 16, v164
	v_and_b32_e32 v185, 0xffff0000, v164
	v_lshlrev_b32_e32 v164, 16, v165
	v_and_b32_e32 v165, 0xffff0000, v165
	v_pk_add_f32 v[182:183], v[186:187], v[182:183]
	v_pk_add_f32 v[10:11], v[170:171], v[178:179]
	v_pk_add_f32 v[128:129], v[128:129], v[162:163]
	v_mov_b32_e32 v162, v6
	v_mov_b32_e32 v163, v176
	v_mov_b32_e32 v176, v7
	v_pk_fma_f32 v[0:1], v[184:185], s[6:7], v[0:1] op_sel_hi:[1,0,1]
	v_pk_fma_f32 v[2:3], v[164:165], s[6:7], v[2:3] op_sel_hi:[1,0,1]
	v_pk_add_f32 v[180:181], v[180:181], v[182:183]
	v_pk_add_f32 v[10:11], v[10:11], v[174:175]
	v_pk_add_f32 v[162:163], v[162:163], v[176:177]
	v_pk_mul_f32 v[164:165], v[0:1], v[0:1]
	v_pk_mul_f32 v[184:185], v[2:3], v[2:3]
	v_pk_add_f32 v[10:11], v[180:181], v[10:11]
	v_pk_add_f32 v[128:129], v[128:129], v[162:163]
	v_mov_b32_e32 v162, v2
	v_pk_add_f32 v[10:11], v[10:11], v[128:129]
	v_mov_b32_e32 v128, v0
	v_mov_b32_e32 v129, v164
	v_mov_b32_e32 v164, v1
	v_mov_b32_e32 v163, v184
	v_mov_b32_e32 v184, v3
	v_pk_add_f32 v[128:129], v[128:129], v[164:165]
	v_pk_add_f32 v[162:163], v[162:163], v[184:185]
	ds_bpermute_b32 v168, v151, v166
	v_pk_add_f32 v[128:129], v[128:129], v[162:163]
	ds_bpermute_b32 v169, v151, v167
	v_pk_add_f32 v[10:11], v[10:11], v[128:129]
	ds_bpermute_b32 v128, v151, v10
	ds_bpermute_b32 v129, v151, v11
	v_cndmask_b32_e32 v151, v156, v161, vcc
	s_waitcnt lgkmcnt(2)
	v_pk_add_f32 v[162:163], v[166:167], v[168:169]
	ds_bpermute_b32 v164, v149, v162
	ds_bpermute_b32 v165, v149, v163
	s_waitcnt lgkmcnt(2)
	v_pk_add_f32 v[10:11], v[10:11], v[128:129]
	ds_bpermute_b32 v128, v149, v10
	ds_bpermute_b32 v129, v149, v11
	v_lshl_add_u32 v149, v160, 5, s7
	s_waitcnt lgkmcnt(2)
	v_pk_add_f32 v[162:163], v[162:163], v[164:165]
	v_cndmask_b32_e32 v149, v156, v149, vcc
	ds_write_b64 v151, v[162:163]
	s_waitcnt lgkmcnt(1)
	v_pk_add_f32 v[10:11], v[10:11], v[128:129]
	ds_write_b64 v149, v[10:11]
	s_movk_i32 s6, 0x100
	v_or_b32_e32 v10, s23, v172
	v_cmp_gt_u32_e64 s[6:7], s6, v172
	v_ashrrev_i32_e32 v11, 31, v10
	s_waitcnt lgkmcnt(0)
	s_barrier
	s_and_saveexec_b64 s[14:15], s[6:7]
	s_cbranch_execz .LBB0_1257
	v_lshl_add_u32 v128, v172, 5, 0
	ds_read_b128 v[162:165], v128
	ds_read_b128 v[166:169], v128 offset:16
	s_ashr_i32 s23, s22, 31
	s_waitcnt lgkmcnt(1)
	v_add_f32_e32 v128, v162, v164
	v_add_f32_e32 v129, v163, v165
	v_lshlrev_b64 v[162:163], 5, v[10:11]
	s_waitcnt lgkmcnt(0)
	v_add_f32_e32 v128, v128, v166
	v_add_f32_e32 v129, v129, v167
	v_lshl_add_u64 v[162:163], s[10:11], 0, v[162:163]
	v_add_f32_e32 v128, v128, v168
	v_add_f32_e32 v129, v129, v169
	v_lshl_add_u64 v[162:163], s[22:23], 3, v[162:163]
	global_store_dwordx2 v[162:163], v[128:129], off sc1
